# sample merged GEMM jobs store raw f32 accumulators, sigmoid gating + 3-way sum + bf16 done by all WGs at phase 5 start; hg_pass3 loads issued one item ahead, output-stage loads hoisted
# speedup vs baseline: 1.0944x; 1.0013x over previous
.LBB0_796:
	s_sub_i32 s14, s34, s94
	s_add_i32 s14, s14, -1
	s_load_dwordx2 s[18:19], s[4:5], 0x40
	s_load_dwordx2 s[26:27], s[4:5], 0x70
	s_movk_i32 s2, 0x3c00
	s_mov_b32 s29, 0
	v_mov_b32_e32 v17, 0
	s_mov_b32 s3, 0x800000
	s_mov_b32 s10, 0x3f317217
	s_mov_b32 s11, 0x7f800000
	s_movk_i32 s23, 0x4000
	s_movk_i32 s33, 0x3000
	s_movk_i32 s42, 0x7000
	s_mov_b32 s43, 0xb000
	s_mov_b32 s44, 0xf000
	s_mov_b32 s45, 0x13000
	s_mov_b32 s46, 0x12000
	s_mov_b32 s47, 0x16000
	s_mov_b32 s48, 0x1a000
	s_mov_b32 s49, 0x1e000
	s_mov_b32 s50, 0x22000
	s_mov_b32 s51, 0x21000
	s_mov_b32 s52, 0x25000
	s_mov_b32 s53, 0x29000
	s_mov_b32 s54, 0x2d000
	s_mov_b32 s55, 0x31000
	s_mov_b32 s56, 0x30000
	s_mov_b32 s57, 0x34000
	s_mov_b32 s58, 0x38000
	s_mov_b32 s59, 0x8000
	s_mov_b32 s60, 0x17000
	s_mov_b32 s61, 0x26000
	s_mov_b32 s62, 0x35000
	s_add_i32 s63, 0, 0x19e00
	s_movk_i32 s64, 0x7fff
	s_movk_i32 s65, 0x880
	s_mov_b32 s66, 0x42a00000
	s_movk_i32 s67, 0x1100
	s_movk_i32 s68, 0x90
	s_add_i32 s69, 0, 0x13200
	s_movk_i32 s70, 0x110
	s_add_i32 s71, 0, 0x17a00
	s_mov_b32 s72, 0xffff0000
	s_add_i32 s73, 0, 0x1a600
	v_mov_b32_e32 v20, 0x358637bd
	v_mov_b32_e32 v21, 0x41b17218
	v_mov_b32_e32 v24, 1
	v_and_b32_e32 v176, 15, v156
	v_bfe_u32 v177, v156, 4, 2
	v_lshlrev_b32_e32 v177, 4, v177
	v_lshrrev_b32_e32 v178, 8, v156
	v_lshl_or_b32 v178, v178, 6, v176
	v_bfe_u32 v179, v156, 6, 2
	v_lshl_or_b32 v179, v179, 4, v176
	v_mad_u32_u24 v100, v178, s70, v177
	v_add_u32_e32 v100, 0x1a800, v100
	v_mad_u32_u24 v101, v178, s68, v177
	v_add_u32_e32 v101, 0x13200, v101
	v_mad_u32_u24 v102, v179, s68, v177
	v_add_u32_e32 v102, 0x17a00, v102
	v_mad_u32_u24 v103, v179, s70, v177
	v_add_u32_e32 v103, 0x4400, v103
	v_lshrrev_b32_e32 v96, 4, v156
	v_and_b32_e32 v97, 15, v156
	v_lshlrev_b32_e32 v97, 4, v97
	v_mad_u32_u24 v96, v96, s70, v97
	v_add_u32_e32 v96, 0x1a800, v96
	v_lshlrev_b32_e32 v97, 4, v156
	s_waitcnt lgkmcnt(0)
	s_mov_b32 s98, s14
	s_lshr_b32 s99, s98, 7
	s_lshl_b32 s99, s99, 11
	s_lshl_b32 s100, s98, 6
	s_and_b32 s100, s100, 0x7c0
	s_or_b32 s99, s99, s100
	s_lshl_b32 s100, s98, 2
	s_and_b32 s100, s100, 0x180
	v_lshrrev_b32_e32 v176, 7, v156
	v_lshl_add_u32 v176, v176, 4, s99
	v_and_b32_e32 v178, 0x7f, v156
	v_or_b32_e32 v177, s100, v178
	v_lshlrev_b32_e32 v177, 2, v177
	global_load_dword v232, v177, s[18:19] offset:2048
	global_load_dword v233, v177, s[18:19]
	s_lshl_b32 s100, s100, 1
	v_lshl_add_u32 v178, v178, 1, s100
	v_mov_b32_e32 v179, 0
	v_lshl_add_u64 v[152:153], v[178:179], 0, s[24:25]
	v_mad_u64_u32 v[152:153], vcc, v176, s2, v[152:153]
	s_lshl_b32 s100, s98, 15
	s_add_u32 s100, s16, s100
	s_addc_u32 s101, s17, 0
	global_load_dwordx4 v[160:163], v97, s[100:101]
	s_add_u32 s100, s100, 0x2000
	s_addc_u32 s101, s101, 0
	global_load_dwordx4 v[164:167], v97, s[100:101]
	s_add_u32 s100, s100, 0x2000
	s_addc_u32 s101, s101, 0
	global_load_dwordx4 v[168:171], v97, s[100:101]
	s_add_u32 s100, s100, 0x2000
	s_addc_u32 s101, s101, 0
	global_load_dwordx4 v[172:175], v97, s[100:101]
	s_mov_b32 s100, 0x3c00
	s_mov_b32 s101, 0
	global_load_ushort v104, v[152:153], off
	global_load_ushort v105, v[152:153], off offset:1024
	global_load_ushort v106, v[152:153], off offset:2048
	v_lshl_add_u64 v[154:155], v[152:153], 0, s[100:101]
	global_load_ushort v107, v[154:155], off
	global_load_ushort v108, v[154:155], off offset:1024
	global_load_ushort v109, v[154:155], off offset:2048
	v_lshl_add_u64 v[158:159], v[154:155], 0, s[100:101]
	global_load_ushort v110, v[158:159], off
	global_load_ushort v111, v[158:159], off offset:1024
	global_load_ushort v112, v[158:159], off offset:2048
	v_lshl_add_u64 v[154:155], v[158:159], 0, s[100:101]
	global_load_ushort v113, v[154:155], off
	global_load_ushort v114, v[154:155], off offset:1024
	global_load_ushort v115, v[154:155], off offset:2048
	v_lshl_add_u64 v[158:159], v[154:155], 0, s[100:101]
	global_load_ushort v116, v[158:159], off
	global_load_ushort v117, v[158:159], off offset:1024
	global_load_ushort v118, v[158:159], off offset:2048
	v_lshl_add_u64 v[154:155], v[158:159], 0, s[100:101]
	global_load_ushort v119, v[154:155], off
	global_load_ushort v120, v[154:155], off offset:1024
	global_load_ushort v121, v[154:155], off offset:2048
	v_lshl_add_u64 v[158:159], v[154:155], 0, s[100:101]
	global_load_ushort v122, v[158:159], off
	global_load_ushort v123, v[158:159], off offset:1024
	global_load_ushort v124, v[158:159], off offset:2048
	v_lshl_add_u64 v[154:155], v[158:159], 0, s[100:101]
	global_load_ushort v125, v[154:155], off
	global_load_ushort v126, v[154:155], off offset:1024
	global_load_ushort v127, v[154:155], off offset:2048
	v_lshl_add_u64 v[158:159], v[154:155], 0, s[100:101]
	global_load_ushort v128, v[158:159], off
	global_load_ushort v129, v[158:159], off offset:1024
	global_load_ushort v130, v[158:159], off offset:2048
	v_lshl_add_u64 v[154:155], v[158:159], 0, s[100:101]
	global_load_ushort v131, v[154:155], off
	global_load_ushort v132, v[154:155], off offset:1024
	global_load_ushort v133, v[154:155], off offset:2048
	v_lshl_add_u64 v[158:159], v[154:155], 0, s[100:101]
	global_load_ushort v134, v[158:159], off
	global_load_ushort v135, v[158:159], off offset:1024
	global_load_ushort v136, v[158:159], off offset:2048
	v_lshl_add_u64 v[154:155], v[158:159], 0, s[100:101]
	global_load_ushort v137, v[154:155], off
	global_load_ushort v138, v[154:155], off offset:1024
	global_load_ushort v139, v[154:155], off offset:2048
	v_lshl_add_u64 v[158:159], v[154:155], 0, s[100:101]
	global_load_ushort v140, v[158:159], off
	global_load_ushort v141, v[158:159], off offset:1024
	global_load_ushort v142, v[158:159], off offset:2048
	v_lshl_add_u64 v[154:155], v[158:159], 0, s[100:101]
	global_load_ushort v143, v[154:155], off
	global_load_ushort v144, v[154:155], off offset:1024
	global_load_ushort v145, v[154:155], off offset:2048
	v_lshl_add_u64 v[158:159], v[154:155], 0, s[100:101]
	global_load_ushort v146, v[158:159], off
	global_load_ushort v147, v[158:159], off offset:1024
	global_load_ushort v148, v[158:159], off offset:2048
	v_lshl_add_u64 v[154:155], v[158:159], 0, s[100:101]
	global_load_ushort v149, v[154:155], off
	global_load_ushort v150, v[154:155], off offset:1024
	global_load_ushort v151, v[154:155], off offset:2048
	s_branch .LBB0_798
.LBB0_797:
	s_or_b64 exec, exec, s[4:5]
	v_or_b32_e32 v16, s30, v32
	v_mov_b64_e32 v[28:29], s[24:25]
	v_mad_u64_u32 v[34:35], s[4:5], v16, s2, v[28:29]
	s_lshl_b32 s4, s74, 2
	v_or_b32_e32 v38, v26, v18
	s_add_u32 s4, s26, s4
	s_mul_i32 s6, s31, 0x3c00
	s_addc_u32 s5, s27, 0
	v_ashrrev_i32_e32 v39, 31, v38
	v_add_u32_e32 v35, s6, v35
	s_waitcnt lgkmcnt(0)
	v_lshl_add_u64 v[18:19], v[38:39], 2, s[4:5]
	s_barrier
	s_waitcnt vmcnt(54)
	v_mov_b32_e32 v26, v208
	v_mov_b32_e32 v27, v209
	v_mov_b32_e32 v28, v210
	v_mov_b32_e32 v29, v211
	v_lshl_add_u64 v[34:35], v[34:35], 0, s[28:29]
	v_lshl_add_u64 v[40:41], v[38:39], 1, v[34:35]
	v_mov_b32_e32 v34, v212
	v_mov_b32_e32 v35, v213
	v_mov_b32_e32 v36, v214
	v_mov_b32_e32 v37, v215
	v_mov_b32_e32 v42, v224
	v_mov_b32_e32 v43, v225
	v_mov_b32_e32 v44, v226
	v_mov_b32_e32 v45, v227
	v_lshl_add_u32 v16, v32, 3, 0
	v_mov_b32_e32 v46, v12
	v_add_u32_e32 v12, 0x1a600, v16
	ds_read_b64 v[32:33], v12
	v_mov_b32_e32 v12, v8
	v_lshl_add_u32 v58, v38, 1, v31
	v_mov_b32_e32 v47, v14
	v_mov_b32_e32 v14, v13
	s_waitcnt lgkmcnt(0)
	v_add_f32_e32 v8, v32, v33
	v_mov_b32_e32 v30, v216
	v_mov_b32_e32 v31, v217
	v_mov_b32_e32 v32, v218
	v_mov_b32_e32 v33, v219
	v_mov_b32_e32 v38, v228
	v_mov_b32_e32 v39, v229
	s_nop 0
	v_mov_b32_e32 v40, v230
	v_mov_b32_e32 v41, v231
	v_fmamk_f32 v8, v8, 0x3c000000, v20
	v_mov_b32_e32 v13, v10
	v_mul_f32_e32 v10, 0x4b800000, v8
	v_cmp_gt_f32_e32 vcc, s3, v8
	s_add_u32 s4, s24, s28
	s_addc_u32 s5, s25, 0
	v_cndmask_b32_e32 v8, v8, v10, vcc
	v_rsq_f32_e32 v8, v8
	s_add_i32 s14, s14, s22
	s_cmpk_lt_i32 s14, 0x400
	v_mul_f32_e32 v10, 0x45800000, v8
	v_cndmask_b32_e32 v16, v8, v10, vcc
	v_pk_mul_f32 v[14:15], v[14:15], v[16:17] op_sel_hi:[1,0]
	v_pk_mul_f32 v[46:47], v[46:47], v[16:17] op_sel_hi:[1,0]
	v_pk_mul_f32 v[12:13], v[12:13], v[16:17] op_sel_hi:[1,0]
	v_mov_b32_e32 v49, v28
	v_mov_b32_e32 v28, v27
	v_lshlrev_b32_e32 v51, 16, v43
	v_lshlrev_b32_e32 v50, 16, v42
	v_and_b32_e32 v43, 0xffff0000, v43
	v_and_b32_e32 v42, 0xffff0000, v42
	v_mov_b32_e32 v48, v26
	v_mov_b32_e32 v26, v34
	v_pk_mul_f32 v[14:15], v[28:29], v[14:15]
	v_lshlrev_b32_e32 v29, 16, v45
	v_mul_f32_e32 v10, 0xbfb8aa3b, v42
	v_mul_f32_e32 v34, 0xbfb8aa3b, v43
	v_lshlrev_b32_e32 v28, 16, v44
	v_and_b32_e32 v44, 0xffff0000, v44
	v_mul_f32_e32 v8, 0xbfb8aa3b, v50
	v_mul_f32_e32 v27, 0xbfb8aa3b, v51
	v_mul_f32_e32 v52, 0xbfb8aa3b, v29
	v_exp_f32_e32 v10, v10
	v_exp_f32_e32 v34, v34
	v_pk_mul_f32 v[46:47], v[48:49], v[46:47]
	v_mul_f32_e32 v48, 0xbfb8aa3b, v28
	v_mul_f32_e32 v49, 0xbfb8aa3b, v44
	v_exp_f32_e32 v8, v8
	v_exp_f32_e32 v27, v27
	v_exp_f32_e32 v52, v52
	v_exp_f32_e32 v48, v48
	v_exp_f32_e32 v49, v49
	v_add_f32_e32 v10, 1.0, v10
	v_add_f32_e32 v34, 1.0, v34
	v_add_f32_e32 v8, 1.0, v8
	v_add_f32_e32 v27, 1.0, v27
	v_add_f32_e32 v57, 1.0, v52
	v_rcp_f32_e32 v52, v10
	v_rcp_f32_e32 v53, v34
	v_add_f32_e32 v54, 1.0, v48
	v_add_f32_e32 v55, 1.0, v49
	v_rcp_f32_e32 v48, v8
	v_rcp_f32_e32 v49, v27
	v_pk_mul_f32 v[42:43], v[52:53], v[42:43]
	v_and_b32_e32 v45, 0xffff0000, v45
	v_pk_mul_f32 v[14:15], v[42:43], v[14:15]
	v_pk_mul_f32 v[48:49], v[48:49], v[50:51]
	v_and_b32_sdwa v27, v15, v24 dst_sel:DWORD dst_unused:UNUSED_PAD src0_sel:WORD_1 src1_sel:DWORD
	v_pk_mul_f32 v[46:47], v[48:49], v[46:47]
	v_add3_u32 v15, v15, v27, s64
	v_and_b32_sdwa v8, v47, v24 dst_sel:DWORD dst_unused:UNUSED_PAD src0_sel:WORD_1 src1_sel:DWORD
	v_add3_u32 v8, v47, v8, s64
	v_and_b32_e32 v15, 0xffff0000, v15
	v_or_b32_sdwa v15, v15, v8 dst_sel:DWORD dst_unused:UNUSED_PAD src0_sel:DWORD src1_sel:WORD_1
	v_mul_f32_e32 v8, 0xbfb8aa3b, v45
	v_rcp_f32_e32 v54, v54
	v_rcp_f32_e32 v56, v55
	v_rcp_f32_e32 v55, v57
	v_exp_f32_e32 v8, v8
	v_and_b32_sdwa v34, v14, v24 dst_sel:DWORD dst_unused:UNUSED_PAD src0_sel:WORD_1 src1_sel:DWORD
	v_and_b32_sdwa v10, v46, v24 dst_sel:DWORD dst_unused:UNUSED_PAD src0_sel:WORD_1 src1_sel:DWORD
	v_add3_u32 v14, v14, v34, s64
	v_add3_u32 v10, v46, v10, s64
	v_and_b32_e32 v14, 0xffff0000, v14
	v_mov_b32_e32 v27, v36
	v_or_b32_sdwa v14, v14, v10 dst_sel:DWORD dst_unused:UNUSED_PAD src0_sel:DWORD src1_sel:WORD_1
	v_pk_mul_f32 v[12:13], v[26:27], v[12:13]
	v_pk_mul_f32 v[26:27], v[54:55], v[28:29]
	v_mov_b32_e32 v10, v9
	v_add_f32_e32 v8, 1.0, v8
	v_pk_mul_f32 v[12:13], v[12:13], v[26:27]
	v_pk_mul_f32 v[26:27], v[10:11], v[16:17] op_sel_hi:[1,0]
	v_rcp_f32_e32 v57, v8
	v_mov_b32_e32 v8, v220
	v_mov_b32_e32 v9, v221
	v_mov_b32_e32 v10, v222
	v_mov_b32_e32 v11, v223
	v_mov_b32_e32 v36, v35
	v_pk_mul_f32 v[18:19], v[36:37], v[26:27]
	v_pk_mul_f32 v[26:27], v[56:57], v[44:45]
	v_mov_b32_e32 v28, v4
	v_pk_mul_f32 v[18:19], v[18:19], v[26:27]
	v_and_b32_sdwa v26, v13, v24 dst_sel:DWORD dst_unused:UNUSED_PAD src0_sel:WORD_1 src1_sel:DWORD
	v_and_b32_sdwa v27, v12, v24 dst_sel:DWORD dst_unused:UNUSED_PAD src0_sel:WORD_1 src1_sel:DWORD
	v_add3_u32 v12, v12, v27, s64
	v_add3_u32 v13, v13, v26, s64
	v_and_b32_sdwa v26, v19, v24 dst_sel:DWORD dst_unused:UNUSED_PAD src0_sel:WORD_1 src1_sel:DWORD
	v_and_b32_sdwa v27, v18, v24 dst_sel:DWORD dst_unused:UNUSED_PAD src0_sel:WORD_1 src1_sel:DWORD
	v_add3_u32 v19, v19, v26, s64
	v_add3_u32 v18, v18, v27, s64
	v_and_b32_e32 v19, 0xffff0000, v19
	v_and_b32_e32 v18, 0xffff0000, v18
	v_or_b32_sdwa v13, v19, v13 dst_sel:DWORD dst_unused:UNUSED_PAD src0_sel:DWORD src1_sel:WORD_1
	v_or_b32_sdwa v12, v18, v12 dst_sel:DWORD dst_unused:UNUSED_PAD src0_sel:DWORD src1_sel:WORD_1
	ds_write2_b64 v58, v[14:15], v[12:13] offset1:4
	v_lshlrev_b32_e32 v12, 16, v38
	v_mul_f32_e32 v14, 0xbfb8aa3b, v12
	v_lshlrev_b32_e32 v13, 16, v39
	v_exp_f32_e32 v15, v14
	v_and_b32_e32 v14, 0xffff0000, v38
	v_mul_f32_e32 v18, 0xbfb8aa3b, v14
	v_mul_f32_e32 v4, 0xbfb8aa3b, v13
	v_exp_f32_e32 v19, v18
	v_exp_f32_e32 v4, v4
	v_add_f32_e32 v15, 1.0, v15
	v_rcp_f32_e32 v18, v15
	v_and_b32_e32 v15, 0xffff0000, v39
	v_add_f32_e32 v19, 1.0, v19
	v_add_f32_e32 v4, 1.0, v4
	v_rcp_f32_e32 v26, v19
	v_rcp_f32_e32 v19, v4
	v_mul_f32_e32 v4, 0xbfb8aa3b, v15
	v_exp_f32_e32 v4, v4
	v_mov_b32_e32 v29, v6
	v_pk_mul_f32 v[28:29], v[28:29], v[16:17] op_sel_hi:[1,0]
	v_mov_b32_e32 v34, v30
	v_add_f32_e32 v4, 1.0, v4
	v_rcp_f32_e32 v27, v4
	v_mov_b32_e32 v35, v32
	v_mov_b32_e32 v6, v5
	v_pk_mul_f32 v[28:29], v[28:29], v[34:35]
	v_pk_mul_f32 v[12:13], v[18:19], v[12:13]
	v_pk_mul_f32 v[4:5], v[6:7], v[16:17] op_sel_hi:[1,0]
	v_mov_b32_e32 v32, v31
	v_pk_mul_f32 v[12:13], v[28:29], v[12:13]
	v_pk_mul_f32 v[4:5], v[4:5], v[32:33]
	v_pk_mul_f32 v[6:7], v[26:27], v[14:15]
	v_mov_b32_e32 v26, v0
	v_pk_mul_f32 v[4:5], v[4:5], v[6:7]
	v_and_b32_sdwa v7, v12, v24 dst_sel:DWORD dst_unused:UNUSED_PAD src0_sel:WORD_1 src1_sel:DWORD
	v_add3_u32 v7, v12, v7, s64
	v_and_b32_sdwa v12, v5, v24 dst_sel:DWORD dst_unused:UNUSED_PAD src0_sel:WORD_1 src1_sel:DWORD
	v_and_b32_sdwa v6, v13, v24 dst_sel:DWORD dst_unused:UNUSED_PAD src0_sel:WORD_1 src1_sel:DWORD
	v_add3_u32 v5, v5, v12, s64
	v_add3_u32 v6, v13, v6, s64
	v_and_b32_sdwa v13, v4, v24 dst_sel:DWORD dst_unused:UNUSED_PAD src0_sel:WORD_1 src1_sel:DWORD
	v_and_b32_e32 v5, 0xffff0000, v5
	v_add3_u32 v4, v4, v13, s64
	v_or_b32_sdwa v5, v5, v6 dst_sel:DWORD dst_unused:UNUSED_PAD src0_sel:DWORD src1_sel:WORD_1
	v_lshlrev_b32_e32 v6, 16, v40
	v_and_b32_e32 v4, 0xffff0000, v4
	v_mul_f32_e32 v12, 0xbfb8aa3b, v6
	v_or_b32_sdwa v4, v4, v7 dst_sel:DWORD dst_unused:UNUSED_PAD src0_sel:DWORD src1_sel:WORD_1
	v_lshlrev_b32_e32 v7, 16, v41
	v_exp_f32_e32 v13, v12
	v_and_b32_e32 v12, 0xffff0000, v40
	v_mul_f32_e32 v14, 0xbfb8aa3b, v12
	v_mul_f32_e32 v0, 0xbfb8aa3b, v7
	v_exp_f32_e32 v15, v14
	v_exp_f32_e32 v0, v0
	v_add_f32_e32 v13, 1.0, v13
	v_rcp_f32_e32 v14, v13
	v_and_b32_e32 v13, 0xffff0000, v41
	v_add_f32_e32 v15, 1.0, v15
	v_add_f32_e32 v0, 1.0, v0
	v_rcp_f32_e32 v18, v15
	v_rcp_f32_e32 v15, v0
	v_mul_f32_e32 v0, 0xbfb8aa3b, v13
	v_exp_f32_e32 v0, v0
	v_mov_b32_e32 v27, v2
	v_pk_mul_f32 v[26:27], v[26:27], v[16:17] op_sel_hi:[1,0]
	v_mov_b32_e32 v28, v8
	v_add_f32_e32 v0, 1.0, v0
	v_rcp_f32_e32 v19, v0
	v_mov_b32_e32 v29, v10
	v_mov_b32_e32 v2, v1
	v_pk_mul_f32 v[26:27], v[26:27], v[28:29]
	v_pk_mul_f32 v[6:7], v[14:15], v[6:7]
	v_pk_mul_f32 v[0:1], v[2:3], v[16:17] op_sel_hi:[1,0]
	v_mov_b32_e32 v10, v9
	v_pk_mul_f32 v[6:7], v[26:27], v[6:7]
	v_pk_mul_f32 v[0:1], v[0:1], v[10:11]
	v_pk_mul_f32 v[2:3], v[18:19], v[12:13]
	s_nop 0
	v_pk_mul_f32 v[0:1], v[0:1], v[2:3]
	v_and_b32_sdwa v2, v7, v24 dst_sel:DWORD dst_unused:UNUSED_PAD src0_sel:WORD_1 src1_sel:DWORD
	v_and_b32_sdwa v3, v6, v24 dst_sel:DWORD dst_unused:UNUSED_PAD src0_sel:WORD_1 src1_sel:DWORD
	v_add3_u32 v3, v6, v3, s64
	v_add3_u32 v2, v7, v2, s64
	v_and_b32_sdwa v6, v1, v24 dst_sel:DWORD dst_unused:UNUSED_PAD src0_sel:WORD_1 src1_sel:DWORD
	v_and_b32_sdwa v7, v0, v24 dst_sel:DWORD dst_unused:UNUSED_PAD src0_sel:WORD_1 src1_sel:DWORD
	v_add3_u32 v1, v1, v6, s64
	v_add3_u32 v0, v0, v7, s64
	v_and_b32_e32 v1, 0xffff0000, v1
	v_and_b32_e32 v0, 0xffff0000, v0
	v_or_b32_sdwa v1, v1, v2 dst_sel:DWORD dst_unused:UNUSED_PAD src0_sel:DWORD src1_sel:WORD_1
	v_or_b32_sdwa v0, v0, v3 dst_sel:DWORD dst_unused:UNUSED_PAD src0_sel:DWORD src1_sel:WORD_1
	ds_write2_b64 v58, v[4:5], v[0:1] offset0:8 offset1:12
	v_lshlrev_b32_e32 v0, 4, v25
	v_and_b32_e32 v16, 0xf0, v0
	v_add_u32_e32 v4, 0, v16
	v_ashrrev_i32_e32 v6, 4, v25
	v_lshl_add_u64 v[8:9], s[4:5], 0, v[16:17]
	v_mad_u64_u32 v[0:1], s[4:5], v6, s70, v[4:5]
	v_ashrrev_i32_e32 v7, 31, v6
	s_waitcnt lgkmcnt(0)
	s_barrier
	ds_read_b128 v[0:3], v0
	v_lshl_add_u64 v[6:7], s[30:31], 0, v[6:7]
	v_mad_u64_u32 v[10:11], s[4:5], v6, s2, v[8:9]
	v_mov_b32_e32 v6, v11
	v_add_u32_e32 v5, 0x200, v25
	v_mad_u64_u32 v[6:7], s[4:5], v7, s2, v[6:7]
	v_ashrrev_i32_e32 v12, 4, v5
	v_mov_b32_e32 v11, v6
	v_mad_u64_u32 v[4:5], s[4:5], v12, s70, v[4:5]
	v_ashrrev_i32_e32 v13, 31, v12
	ds_read_b128 v[4:7], v4
	s_waitcnt lgkmcnt(1)
	global_store_dwordx4 v[10:11], v[0:3], off
	s_nop 1
	v_lshl_add_u64 v[0:1], s[30:31], 0, v[12:13]
	v_mad_u64_u32 v[2:3], s[4:5], v0, s2, v[8:9]
	v_mov_b32_e32 v0, v3
	v_mad_u64_u32 v[0:1], s[4:5], v1, s2, v[0:1]
	v_mov_b32_e32 v3, v0
	s_waitcnt lgkmcnt(0)
	global_store_dwordx4 v[2:3], v[4:7], off
	s_barrier
	s_cbranch_scc0 .LBB0_815
.LBB0_798:
	s_ashr_i32 s4, s14, 7
	v_mov_b32_e32 v25, v156
	s_ashr_i32 s5, s4, 31
	s_lshl_b64 s[30:31], s[4:5], 11
	v_ashrrev_i32_e32 v2, 7, v25
	s_lshl_b32 s4, s14, 6
	s_and_b32 s4, s4, 0x7c0
	v_lshlrev_b32_e32 v0, 4, v2
	s_or_b32 s30, s30, s4
	v_ashrrev_i32_e32 v1, 31, v0
	v_lshl_add_u64 v[4:5], s[30:31], 0, v[0:1]
	v_mov_b64_e32 v[6:7], s[24:25]
	v_mad_u64_u32 v[6:7], s[4:5], v4, s2, v[6:7]
	s_lshl_b32 s4, s14, 2
	v_and_b32_e32 v3, 0x7f, v25
	s_and_b32 s74, s4, 0x180
	v_mad_i32_i24 v7, v5, s2, v7
	s_lshl_b32 s28, s74, 1
	v_or_b32_e32 v1, s74, v3
	v_lshl_add_u64 v[4:5], v[6:7], 0, s[28:29]
	v_lshlrev_b32_e32 v16, 1, v3
	v_lshlrev_b32_e32 v1, 2, v1
	v_lshl_add_u64 v[4:5], v[4:5], 0, v[16:17]
	s_waitcnt lgkmcnt(0)
	s_waitcnt vmcnt(0)
	v_mov_b32_e32 v6, v232
	v_mov_b32_e32 v7, v233
	v_mov_b32_e32 v10, v105
	s_nop 0
	v_mov_b32_e32 v1, v106
	v_mov_b32_e32 v11, v104
	v_add_co_u32_e32 v12, vcc, s23, v4
	s_waitcnt vmcnt(3)
	v_sub_f32_e32 v6, v6, v7
	v_addc_co_u32_e32 v13, vcc, 0, v5, vcc
	v_add_co_u32_e32 v14, vcc, s42, v4
	v_mul_f32_e32 v6, 0x3fb8aa3b, v6
	s_nop 0
	v_addc_co_u32_e32 v15, vcc, 0, v5, vcc
	v_mov_b32_e32 v28, v108
	v_mov_b32_e32 v29, v111
	v_add_co_u32_e32 v8, vcc, s33, v4
	v_exp_f32_e32 v6, v6
	s_nop 0
	v_addc_co_u32_e32 v9, vcc, 0, v5, vcc
	v_add_co_u32_e32 v18, vcc, s43, v4
	v_add_f32_e32 v6, 1.0, v6
	s_nop 0
	v_addc_co_u32_e32 v19, vcc, 0, v5, vcc
	v_add_co_u32_e32 v26, vcc, s44, v4
	s_waitcnt vmcnt(4)
	v_lshlrev_b32_e32 v7, 16, v10
	v_addc_co_u32_e32 v27, vcc, 0, v5, vcc
	v_mov_b32_e32 v30, v107
	v_mov_b32_e32 v31, v114
	v_mov_b32_e32 v32, v117
	s_nop 0
	v_mov_b32_e32 v8, v115
	s_nop 0
	v_mov_b32_e32 v18, v113
	s_nop 0
	v_mov_b32_e32 v19, v110
	v_mov_b32_e32 v9, v109
	v_div_scale_f32 v12, s[4:5], v6, v6, 1.0
	v_rcp_f32_e32 v14, v12
	v_mul_f32_e32 v7, 0xbfb8aa3b, v7
	v_exp_f32_e32 v7, v7
	v_div_scale_f32 v13, vcc, 1.0, v6, 1.0
	v_fma_f32 v15, -v12, v14, 1.0
	v_fmac_f32_e32 v14, v15, v14
	v_mul_f32_e32 v15, v13, v14
	v_add_f32_e32 v7, 1.0, v7
	v_rcp_f32_e32 v7, v7
	s_waitcnt vmcnt(9)
	v_lshlrev_b32_e32 v68, 16, v11
	s_waitcnt vmcnt(8)
	v_lshlrev_b32_e32 v10, 16, v28
	v_mul_f32_e32 v10, 0xbfb8aa3b, v10
	v_exp_f32_e32 v10, v10
	v_fma_f32 v28, -v12, v15, v13
	v_fmac_f32_e32 v15, v28, v14
	v_fma_f32 v12, -v12, v15, v13
	v_add_f32_e32 v10, 1.0, v10
	v_div_fmas_f32 v12, v12, v14, v15
	v_rcp_f32_e32 v10, v10
	v_div_fixup_f32 v51, v12, v6, 1.0
	v_sub_f32_e32 v48, 1.0, v51
	v_fma_f32 v6, v48, v7, v51
	v_cmp_gt_f32_e32 vcc, s3, v6
	v_fma_f32 v12, v48, v10, v51
	v_cmp_gt_f32_e64 s[4:5], s3, v12
	v_cndmask_b32_e64 v7, 0, 32, vcc
	v_ldexp_f32 v7, v6, v7
	v_cndmask_b32_e64 v10, 0, 32, s[4:5]
	v_log_f32_e32 v7, v7
	v_ldexp_f32 v10, v12, v10
	v_log_f32_e32 v13, v10
	s_waitcnt vmcnt(7)
	v_lshlrev_b32_e32 v11, 16, v29
	v_mul_f32_e32 v14, 0x3f317217, v7
	v_fma_f32 v14, v7, s10, -v14
	v_mul_f32_e32 v15, 0x3f317217, v13
	v_fmac_f32_e32 v14, 0x3377d1cf, v7
	v_sub_f32_e32 v10, 1.0, v6
	v_cndmask_b32_e32 v6, 0, v21, vcc
	v_fma_f32 v15, v13, s10, -v15
	v_fmac_f32_e32 v14, 0x3f317217, v7
	v_cmp_lt_f32_e64 vcc, |v7|, s11
	v_mul_f32_e32 v11, 0xbfb8aa3b, v11
	v_fmac_f32_e32 v15, 0x3377d1cf, v13
	v_cndmask_b32_e32 v7, v7, v14, vcc
	v_exp_f32_e32 v11, v11
	v_fmac_f32_e32 v15, 0x3f317217, v13
	v_cmp_lt_f32_e64 vcc, |v13|, s11
	v_sub_f32_e32 v6, v7, v6
	v_add_f32_e32 v37, 0, v6
	v_cndmask_b32_e32 v13, v13, v15, vcc
	v_add_co_u32_e32 v6, vcc, s45, v4
	v_add_f32_e32 v11, 1.0, v11
	s_nop 0
	v_addc_co_u32_e32 v7, vcc, 0, v5, vcc
	v_mov_b32_e32 v28, v120
	v_rcp_f32_e32 v11, v11
	v_cndmask_b32_e64 v14, 0, v21, s[4:5]
	v_sub_f32_e32 v13, v13, v14
	v_add_f32_e32 v39, v37, v13
	v_fma_f32 v29, v48, v11, v51
	v_cmp_gt_f32_e32 vcc, s3, v29
	s_waitcnt vmcnt(7)
	v_lshlrev_b32_e32 v69, 16, v30
	s_waitcnt vmcnt(2)
	v_lshlrev_b32_e32 v70, 16, v19
	v_cndmask_b32_e64 v11, 0, 32, vcc
	v_ldexp_f32 v11, v29, v11
	v_log_f32_e32 v33, v11
	v_sub_f32_e32 v11, 1.0, v12
	v_lshlrev_b32_e32 v12, 16, v31
	v_mul_f32_e32 v31, 0xbfb8aa3b, v12
	v_add_co_u32_e64 v12, s[4:5], s46, v4
	v_mul_f32_e32 v30, 0x3f317217, v33
	s_nop 0
	v_addc_co_u32_e64 v13, s[4:5], 0, v5, s[4:5]
	v_add_co_u32_e64 v14, s[4:5], s47, v4
	v_lshlrev_b32_e32 v71, 16, v18
	s_nop 0
	v_addc_co_u32_e64 v15, s[4:5], 0, v5, s[4:5]
	v_mov_b32_e32 v34, v119
	v_mov_b32_e32 v35, v123
	v_mov_b32_e32 v36, v122
	s_nop 0
	v_mov_b32_e32 v13, v121
	v_mov_b32_e32 v12, v118
	v_mov_b32_e32 v38, v116
	v_exp_f32_e32 v6, v31
	v_cndmask_b32_e32 v14, 0, v21, vcc
	v_fma_f32 v7, v33, s10, -v30
	v_fmac_f32_e32 v7, 0x3377d1cf, v33
	v_add_f32_e32 v6, 1.0, v6
	v_rcp_f32_e32 v6, v6
	v_fmac_f32_e32 v7, 0x3f317217, v33
	v_cmp_lt_f32_e64 s[4:5], |v33|, s11
	v_lshlrev_b32_e32 v27, 16, v32
	v_fma_f32 v15, v48, v6, v51
	v_cmp_gt_f32_e32 vcc, s3, v15
	v_cndmask_b32_e64 v7, v33, v7, s[4:5]
	v_sub_f32_e32 v7, v7, v14
	v_cndmask_b32_e64 v6, 0, 32, vcc
	v_ldexp_f32 v6, v15, v6
	v_log_f32_e32 v26, v6
	v_add_f32_e32 v41, v39, v7
	v_sub_f32_e32 v14, 1.0, v29
	v_mul_f32_e32 v27, 0xbfb8aa3b, v27
	v_mul_f32_e32 v6, 0x3f317217, v26
	v_fma_f32 v19, v26, s10, -v6
	v_add_co_u32_e64 v6, s[4:5], s48, v4
	v_exp_f32_e32 v27, v27
	s_nop 0
	v_addc_co_u32_e64 v7, s[4:5], 0, v5, s[4:5]
	v_mov_b32_e32 v29, v126
	v_fmac_f32_e32 v19, 0x3377d1cf, v26
	v_fmac_f32_e32 v19, 0x3f317217, v26
	v_cmp_lt_f32_e64 s[4:5], |v26|, s11
	v_sub_f32_e32 v15, 1.0, v15
	s_waitcnt vmcnt(7)
	v_lshlrev_b32_e32 v28, 16, v28
	v_cndmask_b32_e64 v19, v26, v19, s[4:5]
	v_cndmask_b32_e32 v26, 0, v21, vcc
	v_sub_f32_e32 v19, v19, v26
	v_add_f32_e32 v26, 1.0, v27
	v_rcp_f32_e32 v26, v26
	v_mul_f32_e32 v28, 0xbfb8aa3b, v28
	v_add_f32_e32 v43, v41, v19
	v_exp_f32_e32 v28, v28
	v_fma_f32 v30, v48, v26, v51
	v_add_co_u32_e64 v26, s[4:5], s49, v4
	v_cmp_gt_f32_e32 vcc, s3, v30
	s_nop 0
	v_addc_co_u32_e64 v27, s[4:5], 0, v5, s[4:5]
	v_mov_b32_e32 v31, v129
	v_cndmask_b32_e64 v18, 0, 32, vcc
	v_ldexp_f32 v18, v30, v18
	v_log_f32_e32 v18, v18
	s_waitcnt vmcnt(7)
	v_lshlrev_b32_e32 v73, 16, v34
	v_mul_f32_e32 v19, 0x3f317217, v18
	v_fma_f32 v19, v18, s10, -v19
	v_fmac_f32_e32 v19, 0x3377d1cf, v18
	v_fmac_f32_e32 v19, 0x3f317217, v18
	v_cmp_lt_f32_e64 s[4:5], |v18|, s11
	s_waitcnt vmcnt(2)
	v_lshlrev_b32_e32 v72, 16, v38
	v_lshlrev_b32_e32 v74, 16, v36
	v_cndmask_b32_e64 v18, v18, v19, s[4:5]
	v_add_f32_e32 v19, 1.0, v28
	v_rcp_f32_e32 v19, v19
	v_cndmask_b32_e32 v28, 0, v21, vcc
	v_sub_f32_e32 v18, v18, v28
	v_add_f32_e32 v49, v43, v18
	v_fma_f32 v28, v48, v19, v51
	v_cmp_gt_f32_e32 vcc, s3, v28
	s_waitcnt vmcnt(1)
	v_lshlrev_b32_e32 v29, 16, v29
	v_cndmask_b32_e64 v18, 0, 32, vcc
	v_ldexp_f32 v18, v28, v18
	v_log_f32_e32 v32, v18
	v_add_co_u32_e64 v18, s[4:5], s50, v4
	v_mul_f32_e32 v29, 0xbfb8aa3b, v29
	s_nop 0
	v_addc_co_u32_e64 v19, s[4:5], 0, v5, s[4:5]
	v_mov_b32_e32 v40, v132
	s_nop 0
	v_mov_b32_e32 v19, v133
	s_nop 0
	v_mov_b32_e32 v18, v130
	v_mov_b32_e32 v42, v128
	s_nop 0
	v_mov_b32_e32 v26, v127
	v_mov_b32_e32 v44, v125
	v_lshlrev_b32_e32 v7, 16, v35
	v_mul_f32_e32 v7, 0xbfb8aa3b, v7
	v_exp_f32_e32 v7, v7
	v_mul_f32_e32 v6, 0x3f317217, v32
	v_fma_f32 v6, v32, s10, -v6
	v_fmac_f32_e32 v6, 0x3377d1cf, v32
	v_add_f32_e32 v7, 1.0, v7
	v_rcp_f32_e32 v7, v7
	v_fmac_f32_e32 v6, 0x3f317217, v32
	v_cmp_lt_f32_e64 s[4:5], |v32|, s11
	v_sub_f32_e32 v27, 1.0, v30
	v_cndmask_b32_e32 v30, 0, v21, vcc
	v_cndmask_b32_e64 v6, v32, v6, s[4:5]
	v_sub_f32_e32 v6, v6, v30
	v_fma_f32 v30, v48, v7, v51
	v_cmp_gt_f32_e32 vcc, s3, v30
	v_add_f32_e32 v53, v49, v6
	v_exp_f32_e32 v29, v29
	v_cndmask_b32_e64 v7, 0, 32, vcc
	v_ldexp_f32 v7, v30, v7
	v_log_f32_e32 v7, v7
	v_cndmask_b32_e32 v33, 0, v21, vcc
	v_sub_f32_e32 v28, 1.0, v28
	v_mul_f32_e32 v6, 0x3f317217, v7
	v_fma_f32 v6, v7, s10, -v6
	v_fmac_f32_e32 v6, 0x3377d1cf, v7
	v_fmac_f32_e32 v6, 0x3f317217, v7
	v_cmp_lt_f32_e64 s[4:5], |v7|, s11
	s_waitcnt vmcnt(2)
	v_lshlrev_b32_e32 v76, 16, v42
	v_cndmask_b32_e64 v32, v7, v6, s[4:5]
	v_add_f32_e32 v6, 1.0, v29
	v_rcp_f32_e32 v29, v6
	v_add_co_u32_e32 v6, vcc, s52, v4
	v_sub_f32_e32 v32, v32, v33
	s_nop 0
	v_addc_co_u32_e32 v7, vcc, 0, v5, vcc
	v_mov_b32_e32 v34, v135
	v_fma_f32 v35, v48, v29, v51
	v_cmp_gt_f32_e32 vcc, s3, v35
	v_add_f32_e32 v54, v53, v32
	s_waitcnt vmcnt(1)
	v_lshlrev_b32_e32 v75, 16, v44
	v_cndmask_b32_e64 v29, 0, 32, vcc
	v_ldexp_f32 v29, v35, v29
	v_log_f32_e32 v38, v29
	v_sub_f32_e32 v29, 1.0, v30
	v_lshlrev_b32_e32 v30, 16, v31
	v_mul_f32_e32 v30, 0xbfb8aa3b, v30
	v_exp_f32_e32 v45, v30
	v_add_co_u32_e64 v30, s[4:5], s51, v4
	v_mul_f32_e32 v36, 0x3f317217, v38
	s_nop 0
	v_addc_co_u32_e64 v31, s[4:5], 0, v5, s[4:5]
	v_add_co_u32_e64 v32, s[4:5], s53, v4
	v_mov_b32_e32 v50, v131
	s_nop 0
	v_addc_co_u32_e64 v33, s[4:5], 0, v5, s[4:5]
	v_mov_b32_e32 v52, v138
	v_fma_f32 v30, v38, s10, -v36
	v_fmac_f32_e32 v30, 0x3377d1cf, v38
	v_fmac_f32_e32 v30, 0x3f317217, v38
	v_cmp_lt_f32_e64 s[4:5], |v38|, s11
	v_cndmask_b32_e32 v36, 0, v21, vcc
	v_add_f32_e32 v31, 1.0, v45
	v_cndmask_b32_e64 v30, v38, v30, s[4:5]
	v_sub_f32_e32 v30, v30, v36
	v_add_f32_e32 v55, v54, v30
	v_lshlrev_b32_e32 v30, 16, v40
	v_add_co_u32_e64 v44, s[4:5], s54, v4
	v_mul_f32_e32 v40, 0xbfb8aa3b, v30
	s_nop 0
	v_addc_co_u32_e64 v45, s[4:5], 0, v5, s[4:5]
	v_rcp_f32_e32 v31, v31
	v_mov_b32_e32 v59, v141
	v_mov_b32_e32 v61, v140
	v_mov_b32_e32 v30, v139
	v_mov_b32_e32 v60, v137
	v_mov_b32_e32 v62, v134
	v_exp_f32_e32 v6, v40
	v_fma_f32 v36, v48, v31, v51
	v_cmp_gt_f32_e32 vcc, s3, v36
	v_add_f32_e32 v6, 1.0, v6
	v_rcp_f32_e32 v6, v6
	v_cndmask_b32_e64 v31, 0, 32, vcc
	v_ldexp_f32 v31, v36, v31
	v_log_f32_e32 v38, v31
	v_fma_f32 v33, v48, v6, v51
	v_cndmask_b32_e32 v32, 0, v21, vcc
	v_cmp_gt_f32_e32 vcc, s3, v33
	v_sub_f32_e32 v31, 1.0, v35
	v_mul_f32_e32 v35, 0x3f317217, v38
	v_cndmask_b32_e64 v6, 0, 32, vcc
	v_ldexp_f32 v6, v33, v6
	v_fma_f32 v7, v38, s10, -v35
	v_log_f32_e32 v35, v6
	v_fmac_f32_e32 v7, 0x3377d1cf, v38
	v_fmac_f32_e32 v7, 0x3f317217, v38
	v_cmp_lt_f32_e64 s[4:5], |v38|, s11
	v_mul_f32_e32 v6, 0x3f317217, v35
	v_sub_f32_e32 v33, 1.0, v33
	v_cndmask_b32_e64 v7, v38, v7, s[4:5]
	v_sub_f32_e32 v7, v7, v32
	v_sub_f32_e32 v32, 1.0, v36
	v_fma_f32 v36, v35, s10, -v6
	v_add_co_u32_e64 v6, s[4:5], s55, v4
	v_add_f32_e32 v56, v55, v7
	s_nop 0
	v_addc_co_u32_e64 v7, s[4:5], 0, v5, s[4:5]
	v_mov_b32_e32 v40, v144
	v_fmac_f32_e32 v36, 0x3377d1cf, v35
	v_fmac_f32_e32 v36, 0x3f317217, v35
	v_cmp_lt_f32_e64 s[4:5], |v35|, s11
	s_waitcnt vmcnt(8)
	v_lshlrev_b32_e32 v34, 16, v34
	v_mul_f32_e32 v34, 0xbfb8aa3b, v34
	v_exp_f32_e32 v34, v34
	v_cndmask_b32_e64 v35, v35, v36, s[4:5]
	v_cndmask_b32_e32 v36, 0, v21, vcc
	v_sub_f32_e32 v35, v35, v36
	v_add_f32_e32 v34, 1.0, v34
	v_rcp_f32_e32 v34, v34
	v_add_co_u32_e64 v46, s[4:5], s57, v4
	v_add_f32_e32 v57, v56, v35
	v_fma_f32 v36, v48, v34, v51
	v_cmp_gt_f32_e32 vcc, s3, v36
	v_addc_co_u32_e64 v47, s[4:5], 0, v5, s[4:5]
	s_nop 0
	v_cndmask_b32_e64 v34, 0, 32, vcc
	v_mov_b32_e32 v42, v147
	v_ldexp_f32 v34, v36, v34
	v_log_f32_e32 v38, v34
	s_waitcnt vmcnt(8)
	v_lshlrev_b32_e32 v77, 16, v50
	s_waitcnt vmcnt(7)
	v_lshlrev_b32_e32 v35, 16, v52
	v_mul_f32_e32 v35, 0xbfb8aa3b, v35
	v_exp_f32_e32 v35, v35
	v_mul_f32_e32 v34, 0x3f317217, v38
	v_fma_f32 v50, v38, s10, -v34
	v_fmac_f32_e32 v50, 0x3377d1cf, v38
	v_add_f32_e32 v34, 1.0, v35
	v_rcp_f32_e32 v52, v34
	v_add_co_u32_e64 v34, s[4:5], s56, v4
	v_fmac_f32_e32 v50, 0x3f317217, v38
	s_nop 0
	v_addc_co_u32_e64 v35, s[4:5], 0, v5, s[4:5]
	v_add_co_u32_e64 v64, s[4:5], s58, v4
	s_waitcnt vmcnt(5)
	v_lshlrev_b32_e32 v80, 16, v61
	v_addc_co_u32_e64 v65, s[4:5], 0, v5, s[4:5]
	v_mov_b32_e32 v63, v143
	v_mov_b32_e32 v66, v150
	v_cmp_lt_f32_e64 s[4:5], |v38|, s11
	v_cndmask_b32_e32 v35, 0, v21, vcc
	s_waitcnt vmcnt(5)
	v_lshlrev_b32_e32 v79, 16, v60
	v_cndmask_b32_e64 v34, v38, v50, s[4:5]
	v_sub_f32_e32 v34, v34, v35
	v_fma_f32 v35, v48, v52, v51
	v_mov_b32_e32 v52, v149
	s_nop 0
	v_mov_b32_e32 v46, v146
	v_lshlrev_b32_e32 v50, 16, v59
	v_cmp_gt_f32_e32 vcc, s3, v35
	v_mul_f32_e32 v50, 0xbfb8aa3b, v50
	v_exp_f32_e32 v50, v50
	v_cndmask_b32_e64 v38, 0, 32, vcc
	v_ldexp_f32 v38, v35, v38
	v_log_f32_e32 v38, v38
	v_add_f32_e32 v47, 1.0, v50
	v_rcp_f32_e32 v47, v47
	v_add_f32_e32 v58, v57, v34
	v_sub_f32_e32 v34, 1.0, v36
	v_mul_f32_e32 v36, 0x3f317217, v38
	v_fma_f32 v36, v38, s10, -v36
	v_fmac_f32_e32 v36, 0x3377d1cf, v38
	v_fmac_f32_e32 v36, 0x3f317217, v38
	v_cmp_lt_f32_e64 s[4:5], |v38|, s11
	v_fma_f32 v47, v48, v47, v51
	s_waitcnt vmcnt(6)
	v_lshlrev_b32_e32 v78, 16, v62
	v_cndmask_b32_e64 v36, v38, v36, s[4:5]
	v_cndmask_b32_e32 v38, 0, v21, vcc
	v_cmp_gt_f32_e32 vcc, s3, v47
	v_sub_f32_e32 v36, v36, v38
	v_add_f32_e32 v59, v58, v36
	v_cndmask_b32_e64 v38, 0, 32, vcc
	v_ldexp_f32 v38, v47, v38
	v_log_f32_e32 v50, v38
	v_sub_f32_e32 v38, 1.0, v35
	v_mov_b32_e32 v36, v145
	v_mov_b32_e32 v35, v142
	s_waitcnt vmcnt(7)
	v_lshlrev_b32_e32 v6, 16, v40
	v_mul_f32_e32 v6, 0xbfb8aa3b, v6
	v_exp_f32_e32 v6, v6
	v_mul_f32_e32 v60, 0x3f317217, v50
	v_fma_f32 v7, v50, s10, -v60
	v_fmac_f32_e32 v7, 0x3377d1cf, v50
	v_add_f32_e32 v6, 1.0, v6
	v_rcp_f32_e32 v6, v6
	v_fmac_f32_e32 v7, 0x3f317217, v50
	v_cmp_lt_f32_e64 s[4:5], |v50|, s11
	v_cndmask_b32_e32 v40, 0, v21, vcc
	v_fma_f32 v6, v48, v6, v51
	v_cndmask_b32_e64 v7, v50, v7, s[4:5]
	v_cmp_gt_f32_e32 vcc, s3, v6
	v_sub_f32_e32 v7, v7, v40
	v_add_f32_e32 v60, v59, v7
	v_cndmask_b32_e64 v40, 0, 32, vcc
	v_ldexp_f32 v40, v6, v40
	v_log_f32_e32 v44, v40
	v_sub_f32_e32 v40, 1.0, v47
	s_waitcnt vmcnt(6)
	v_lshlrev_b32_e32 v42, 16, v42
	v_mul_f32_e32 v42, 0xbfb8aa3b, v42
	v_exp_f32_e32 v42, v42
	v_mul_f32_e32 v7, 0x3f317217, v44
	v_fma_f32 v7, v44, s10, -v7
	v_fmac_f32_e32 v7, 0x3377d1cf, v44
	v_add_f32_e32 v42, 1.0, v42
	v_rcp_f32_e32 v42, v42
	v_fmac_f32_e32 v7, 0x3f317217, v44
	v_cmp_lt_f32_e64 s[4:5], |v44|, s11
	s_waitcnt vmcnt(5)
	v_lshlrev_b32_e32 v81, 16, v63
	v_cndmask_b32_e64 v7, v44, v7, s[4:5]
	v_cndmask_b32_e32 v44, 0, v21, vcc
	v_sub_f32_e32 v7, v7, v44
	v_fma_f32 v44, v48, v42, v51
	v_add_f32_e32 v61, v60, v7
	s_waitcnt vmcnt(4)
	v_lshlrev_b32_e32 v7, 16, v66
	v_cmp_gt_f32_e32 vcc, s3, v44
	v_mul_f32_e32 v7, 0xbfb8aa3b, v7
	v_exp_f32_e32 v7, v7
	v_cndmask_b32_e64 v42, 0, 32, vcc
	v_ldexp_f32 v42, v44, v42
	v_log_f32_e32 v45, v42
	v_add_f32_e32 v7, 1.0, v7
	v_rcp_f32_e32 v7, v7
	v_sub_f32_e32 v42, 1.0, v6
	v_mul_f32_e32 v6, 0x3f317217, v45
	v_fma_f32 v6, v45, s10, -v6
	v_fmac_f32_e32 v6, 0x3377d1cf, v45
	v_fmac_f32_e32 v6, 0x3f317217, v45
	v_cmp_lt_f32_e64 s[4:5], |v45|, s11
	v_fmac_f32_e32 v51, v48, v7
	s_waitcnt vmcnt(2)
	v_lshlrev_b32_e32 v82, 16, v46
	v_cndmask_b32_e64 v6, v45, v6, s[4:5]
	v_cndmask_b32_e32 v45, 0, v21, vcc
	v_cmp_gt_f32_e32 vcc, s3, v51
	v_sub_f32_e32 v6, v6, v45
	v_add_f32_e32 v62, v61, v6
	v_cndmask_b32_e64 v7, 0, 32, vcc
	v_ldexp_f32 v7, v51, v7
	v_log_f32_e32 v7, v7
	v_sub_f32_e32 v44, 1.0, v44
	v_sub_f32_e32 v51, 1.0, v51
	v_mul_f32_e32 v6, 0x3f317217, v7
	v_fma_f32 v6, v7, s10, -v6
	v_fmac_f32_e32 v6, 0x3377d1cf, v7
	v_fmac_f32_e32 v6, 0x3f317217, v7
	v_cmp_lt_f32_e64 s[4:5], |v7|, s11
	s_nop 1
	v_cndmask_b32_e64 v6, v7, v6, s[4:5]
	v_cndmask_b32_e32 v7, 0, v21, vcc
	v_sub_f32_e32 v6, v6, v7
	v_add_f32_e32 v63, v62, v6
	v_add_co_u32_e32 v6, vcc, s59, v4
	s_nop 1
	v_addc_co_u32_e32 v7, vcc, 0, v5, vcc
	v_add_co_u32_e32 v46, vcc, s60, v4
	s_nop 1
	v_addc_co_u32_e32 v47, vcc, 0, v5, vcc
	v_add_co_u32_e32 v66, vcc, s61, v4
	s_nop 1
	v_addc_co_u32_e32 v67, vcc, 0, v5, vcc
	v_add_co_u32_e32 v4, vcc, s62, v4
	s_nop 1
	v_addc_co_u32_e32 v5, vcc, 0, v5, vcc
	v_mov_b32_e32 v50, v112
	v_mov_b32_e32 v48, v124
	s_nop 0
	v_mov_b32_e32 v46, v136
	v_mov_b32_e32 v45, v148
	v_mov_b32_e32 v47, v151
	v_lshl_add_u32 v4, v25, 2, s63
	v_lshl_add_u32 v6, v3, 2, s63
	ds_write_b32 v4, v63
	s_waitcnt lgkmcnt(0)
	s_barrier
	ds_read2st64_b32 v[4:5], v6 offset1:2
	v_lshlrev_b32_e32 v64, 16, v52
	ds_read_b32 v52, v6 offset:1024
	v_cmp_lt_i32_e32 vcc, 0, v2
	v_mul_lo_u32 v66, v2, s65
	v_or_b32_e32 v66, v66, v3
	s_waitcnt lgkmcnt(1)
	v_cndmask_b32_e32 v4, 0, v4, vcc
	v_cmp_lt_i32_e32 vcc, 1, v2
	v_lshl_add_u32 v66, v66, 1, 0
	s_nop 0
	v_cndmask_b32_e32 v6, 0, v5, vcc
	v_cmp_lt_i32_e32 vcc, 2, v2
	v_add_f32_e32 v4, v4, v6
	s_waitcnt lgkmcnt(0)
	v_cndmask_b32_e32 v6, 0, v52, vcc
	v_add_f32_e32 v4, v4, v6
	v_mul_f32_e32 v4, 0x3fb8aa3b, v4
	v_mad_u64_u32 v[6:7], s[4:5], v2, v2, v[2:3]
	v_exp_f32_e32 v65, v4
	v_lshrrev_b32_e32 v4, 31, v6
	v_add_u32_e32 v4, v6, v4
	v_mul_f32_e32 v6, 0x3fb8aa3b, v37
	v_exp_f32_e32 v6, v6
	v_lshrrev_b32_e32 v4, 1, v4
	v_add_u32_e32 v7, v4, v2
	v_add_u32_e32 v4, 0, v16
	v_mul_f32_e32 v6, v6, v68
	v_bfe_u32 v16, v6, 16, 1
	v_add3_u32 v16, v6, v16, s64
	ds_write_b16_d16_hi v66, v16
	v_min_f32_e64 v16, -v37, s66
	v_mul_f32_e32 v16, 0x3fb8aa3b, v16
	v_exp_f32_e32 v16, v16
	v_mul_f32_e32 v6, v6, v65
	v_bfe_u32 v67, v6, 16, 1
	v_add3_u32 v6, v6, v67, s64
	ds_write_b16_d16_hi v66, v6 offset:17408
	v_mul_f32_e32 v6, v10, v16
	v_bfe_u32 v16, v6, 16, 1
	v_add3_u32 v16, v6, v16, s64
	v_mul_f32_e32 v6, 0x3fb8aa3b, v39
	v_exp_f32_e32 v67, v6
	v_mad_u64_u32 v[6:7], s[4:5], v7, s67, v[4:5]
	ds_write_b16_d16_hi v6, v16 offset:34816
	v_mul_f32_e32 v7, v67, v69
	v_bfe_u32 v16, v7, 16, 1
	v_add3_u32 v16, v7, v16, s64
	ds_write_b16_d16_hi v66, v16 offset:272
	v_min_f32_e64 v16, -v39, s66
	v_mul_f32_e32 v16, 0x3fb8aa3b, v16
	v_exp_f32_e32 v16, v16
	v_mul_f32_e32 v7, v7, v65
	v_bfe_u32 v67, v7, 16, 1
	v_add3_u32 v7, v7, v67, s64
	ds_write_b16_d16_hi v66, v7 offset:17680
	v_mul_f32_e32 v7, v11, v16
	v_mul_f32_e32 v16, 0x3fb8aa3b, v41
	v_exp_f32_e32 v16, v16
	v_bfe_u32 v67, v7, 16, 1
	v_add3_u32 v7, v7, v67, s64
	ds_write_b16_d16_hi v6, v7 offset:35088
	v_mul_f32_e32 v7, v16, v70
	v_bfe_u32 v16, v7, 16, 1
	v_add3_u32 v16, v7, v16, s64
	ds_write_b16_d16_hi v66, v16 offset:544
	v_min_f32_e64 v16, -v41, s66
	v_mul_f32_e32 v16, 0x3fb8aa3b, v16
	v_exp_f32_e32 v16, v16
	v_mul_f32_e32 v7, v7, v65
	v_bfe_u32 v67, v7, 16, 1
	v_add3_u32 v7, v7, v67, s64
	ds_write_b16_d16_hi v66, v7 offset:17952
	v_mul_f32_e32 v7, v14, v16
	v_mul_f32_e32 v16, 0x3fb8aa3b, v43
	v_exp_f32_e32 v16, v16
	v_bfe_u32 v67, v7, 16, 1
	v_add3_u32 v7, v7, v67, s64
	ds_write_b16_d16_hi v6, v7 offset:35360
	v_mul_f32_e32 v7, v16, v71
	v_bfe_u32 v16, v7, 16, 1
	v_add3_u32 v16, v7, v16, s64
	ds_write_b16_d16_hi v66, v16 offset:816
	v_min_f32_e64 v16, -v43, s66
	v_mul_f32_e32 v16, 0x3fb8aa3b, v16
	v_exp_f32_e32 v16, v16
	v_mul_f32_e32 v7, v7, v65
	v_bfe_u32 v67, v7, 16, 1
	v_add3_u32 v7, v7, v67, s64
	ds_write_b16_d16_hi v66, v7 offset:18224
	v_mul_f32_e32 v7, v15, v16
	v_mul_f32_e32 v16, 0x3fb8aa3b, v49
	v_exp_f32_e32 v16, v16
	v_bfe_u32 v67, v7, 16, 1
	v_add3_u32 v7, v7, v67, s64
	ds_write_b16_d16_hi v6, v7 offset:35632
	v_mul_f32_e32 v7, v16, v72
	v_bfe_u32 v16, v7, 16, 1
	v_add3_u32 v16, v7, v16, s64
	ds_write_b16_d16_hi v66, v16 offset:1088
	v_min_f32_e64 v16, -v49, s66
	v_mul_f32_e32 v16, 0x3fb8aa3b, v16
	v_exp_f32_e32 v16, v16
	v_mul_f32_e32 v7, v7, v65
	v_bfe_u32 v67, v7, 16, 1
	v_add3_u32 v7, v7, v67, s64
	ds_write_b16_d16_hi v66, v7 offset:18496
	v_mul_f32_e32 v7, v27, v16
	v_mul_f32_e32 v16, 0x3fb8aa3b, v53
	v_exp_f32_e32 v16, v16
	v_bfe_u32 v67, v7, 16, 1
	v_add3_u32 v7, v7, v67, s64
	ds_write_b16_d16_hi v6, v7 offset:35904
	v_mul_f32_e32 v7, v16, v73
	v_bfe_u32 v16, v7, 16, 1
	v_add3_u32 v16, v7, v16, s64
	ds_write_b16_d16_hi v66, v16 offset:1360
	v_min_f32_e64 v16, -v53, s66
	v_mul_f32_e32 v16, 0x3fb8aa3b, v16
	v_exp_f32_e32 v16, v16
	v_mul_f32_e32 v7, v7, v65
	v_bfe_u32 v67, v7, 16, 1
	v_add3_u32 v7, v7, v67, s64
	ds_write_b16_d16_hi v66, v7 offset:18768
	v_mul_f32_e32 v7, v28, v16
	v_mul_f32_e32 v16, 0x3fb8aa3b, v54
	v_exp_f32_e32 v16, v16
	v_bfe_u32 v67, v7, 16, 1
	v_add3_u32 v7, v7, v67, s64
	ds_write_b16_d16_hi v6, v7 offset:36176
	v_mul_f32_e32 v7, v16, v74
	v_bfe_u32 v16, v7, 16, 1
	v_add3_u32 v16, v7, v16, s64
	ds_write_b16_d16_hi v66, v16 offset:1632
	v_min_f32_e64 v16, -v54, s66
	v_mul_f32_e32 v16, 0x3fb8aa3b, v16
	v_exp_f32_e32 v16, v16
	v_mul_f32_e32 v7, v7, v65
	v_bfe_u32 v67, v7, 16, 1
	v_add3_u32 v7, v7, v67, s64
	ds_write_b16_d16_hi v66, v7 offset:19040
	v_mul_f32_e32 v7, v29, v16
	v_mul_f32_e32 v16, 0x3fb8aa3b, v55
	v_exp_f32_e32 v16, v16
	v_bfe_u32 v67, v7, 16, 1
	v_add3_u32 v7, v7, v67, s64
	ds_write_b16_d16_hi v6, v7 offset:36448
	v_mul_f32_e32 v7, v16, v75
	v_bfe_u32 v16, v7, 16, 1
	v_add3_u32 v16, v7, v16, s64
	ds_write_b16_d16_hi v66, v16 offset:1904
	v_min_f32_e64 v16, -v55, s66
	v_mul_f32_e32 v16, 0x3fb8aa3b, v16
	v_exp_f32_e32 v16, v16
	v_mul_f32_e32 v7, v7, v65
	v_bfe_u32 v67, v7, 16, 1
	v_add3_u32 v7, v7, v67, s64
	ds_write_b16_d16_hi v66, v7 offset:19312
	v_mul_f32_e32 v7, v31, v16
	v_mul_f32_e32 v16, 0x3fb8aa3b, v56
	v_exp_f32_e32 v16, v16
	v_bfe_u32 v67, v7, 16, 1
	v_add3_u32 v7, v7, v67, s64
	ds_write_b16_d16_hi v6, v7 offset:36720
	v_mul_f32_e32 v7, v16, v76
	v_bfe_u32 v16, v7, 16, 1
	v_add3_u32 v16, v7, v16, s64
	ds_write_b16_d16_hi v66, v16 offset:2176
	v_min_f32_e64 v16, -v56, s66
	v_mul_f32_e32 v16, 0x3fb8aa3b, v16
	v_exp_f32_e32 v16, v16
	v_mul_f32_e32 v7, v7, v65
	v_bfe_u32 v67, v7, 16, 1
	v_add3_u32 v7, v7, v67, s64
	ds_write_b16_d16_hi v66, v7 offset:19584
	v_mul_f32_e32 v7, v32, v16
	v_mul_f32_e32 v16, 0x3fb8aa3b, v57
	v_exp_f32_e32 v16, v16
	v_bfe_u32 v67, v7, 16, 1
	v_add3_u32 v7, v7, v67, s64
	ds_write_b16_d16_hi v6, v7 offset:36992
	v_mul_f32_e32 v7, v16, v77
	v_bfe_u32 v16, v7, 16, 1
	v_add3_u32 v16, v7, v16, s64
	ds_write_b16_d16_hi v66, v16 offset:2448
	v_min_f32_e64 v16, -v57, s66
	v_mul_f32_e32 v16, 0x3fb8aa3b, v16
	v_exp_f32_e32 v16, v16
	v_mul_f32_e32 v7, v7, v65
	v_bfe_u32 v67, v7, 16, 1
	v_add3_u32 v7, v7, v67, s64
	ds_write_b16_d16_hi v66, v7 offset:19856
	v_mul_f32_e32 v7, v33, v16
	v_mul_f32_e32 v16, 0x3fb8aa3b, v58
	v_exp_f32_e32 v16, v16
	v_bfe_u32 v67, v7, 16, 1
	v_add3_u32 v7, v7, v67, s64
	ds_write_b16_d16_hi v6, v7 offset:37264
	v_mul_f32_e32 v7, v16, v78
	v_bfe_u32 v16, v7, 16, 1
	v_add3_u32 v16, v7, v16, s64
	ds_write_b16_d16_hi v66, v16 offset:2720
	v_min_f32_e64 v16, -v58, s66
	v_mul_f32_e32 v16, 0x3fb8aa3b, v16
	v_exp_f32_e32 v16, v16
	v_mul_f32_e32 v7, v7, v65
	v_bfe_u32 v67, v7, 16, 1
	v_add3_u32 v7, v7, v67, s64
	ds_write_b16_d16_hi v66, v7 offset:20128
	v_mul_f32_e32 v7, v34, v16
	v_mul_f32_e32 v16, 0x3fb8aa3b, v59
	v_exp_f32_e32 v16, v16
	v_bfe_u32 v67, v7, 16, 1
	v_add3_u32 v7, v7, v67, s64
	ds_write_b16_d16_hi v6, v7 offset:37536
	v_mul_f32_e32 v7, v16, v79
	v_bfe_u32 v16, v7, 16, 1
	v_add3_u32 v16, v7, v16, s64
	ds_write_b16_d16_hi v66, v16 offset:2992
	v_min_f32_e64 v16, -v59, s66
	v_mul_f32_e32 v16, 0x3fb8aa3b, v16
	v_exp_f32_e32 v16, v16
	v_mul_f32_e32 v7, v7, v65
	v_bfe_u32 v67, v7, 16, 1
	v_add3_u32 v7, v7, v67, s64
	ds_write_b16_d16_hi v66, v7 offset:20400
	v_mul_f32_e32 v7, v38, v16
	v_mul_f32_e32 v16, 0x3fb8aa3b, v60
	v_exp_f32_e32 v16, v16
	v_bfe_u32 v67, v7, 16, 1
	v_add3_u32 v7, v7, v67, s64
	ds_write_b16_d16_hi v6, v7 offset:37808
	v_mul_f32_e32 v7, v16, v80
	v_bfe_u32 v16, v7, 16, 1
	v_add3_u32 v16, v7, v16, s64
	ds_write_b16_d16_hi v66, v16 offset:3264
	v_min_f32_e64 v16, -v60, s66
	v_mul_f32_e32 v16, 0x3fb8aa3b, v16
	v_exp_f32_e32 v16, v16
	v_mul_f32_e32 v7, v7, v65
	v_bfe_u32 v67, v7, 16, 1
	v_add3_u32 v7, v7, v67, s64
	ds_write_b16_d16_hi v66, v7 offset:20672
	v_mul_f32_e32 v7, v40, v16
	v_mul_f32_e32 v16, 0x3fb8aa3b, v61
	v_exp_f32_e32 v16, v16
	v_bfe_u32 v67, v7, 16, 1
	v_add3_u32 v7, v7, v67, s64
	ds_write_b16_d16_hi v6, v7 offset:38080
	v_mul_f32_e32 v7, v16, v81
	v_bfe_u32 v16, v7, 16, 1
	v_add3_u32 v16, v7, v16, s64
	ds_write_b16_d16_hi v66, v16 offset:3536
	v_min_f32_e64 v16, -v61, s66
	v_mul_f32_e32 v16, 0x3fb8aa3b, v16
	v_exp_f32_e32 v16, v16
	v_mul_f32_e32 v7, v7, v65
	v_bfe_u32 v67, v7, 16, 1
	v_add3_u32 v7, v7, v67, s64
	ds_write_b16_d16_hi v66, v7 offset:20944
	v_mul_f32_e32 v7, v42, v16
	v_mul_f32_e32 v16, 0x3fb8aa3b, v62
	v_exp_f32_e32 v16, v16
	v_bfe_u32 v67, v7, 16, 1
	v_add3_u32 v7, v7, v67, s64
	ds_write_b16_d16_hi v6, v7 offset:38352
	v_mul_f32_e32 v7, v16, v82
	v_bfe_u32 v16, v7, 16, 1
	v_add3_u32 v16, v7, v16, s64
	ds_write_b16_d16_hi v66, v16 offset:3808
	v_min_f32_e64 v16, -v62, s66
	v_mul_f32_e32 v16, 0x3fb8aa3b, v16
	v_exp_f32_e32 v16, v16
	v_mul_f32_e32 v7, v7, v65
	v_bfe_u32 v67, v7, 16, 1
	v_add3_u32 v7, v7, v67, s64
	ds_write_b16_d16_hi v66, v7 offset:21216
	v_mul_f32_e32 v7, v44, v16
	v_mul_f32_e32 v16, 0x3fb8aa3b, v63
	v_exp_f32_e32 v16, v16
	v_bfe_u32 v67, v7, 16, 1
	v_add3_u32 v7, v7, v67, s64
	ds_write_b16_d16_hi v6, v7 offset:38624
	v_mul_f32_e32 v7, v16, v64
	v_bfe_u32 v16, v7, 16, 1
	v_add3_u32 v16, v7, v16, s64
	ds_write_b16_d16_hi v66, v16 offset:4080
	v_min_f32_e64 v16, -v63, s66
	v_mul_f32_e32 v16, 0x3fb8aa3b, v16
	v_exp_f32_e32 v16, v16
	v_mul_f32_e32 v7, v7, v65
	v_bfe_u32 v64, v7, 16, 1
	v_add3_u32 v7, v7, v64, s64
	ds_write_b16_d16_hi v66, v7 offset:21488
	v_mul_f32_e32 v7, v51, v16
	v_bfe_u32 v16, v7, 16, 1
	v_add3_u32 v7, v7, v16, s64
	v_cmp_gt_i32_e32 vcc, 3, v2
	ds_write_b16_d16_hi v6, v7 offset:38896
	s_and_saveexec_b64 s[36:37], vcc
	s_cbranch_execz .LBB0_801
	v_cmp_gt_i32_e32 vcc, 1, v2
	v_add_f32_e32 v5, 0, v5
	v_cmp_ne_u32_e64 s[4:5], 2, v2
	v_sub_f32_e32 v6, v63, v37
	v_sub_f32_e32 v7, v63, v39
	v_sub_f32_e32 v16, v63, v41
	v_sub_f32_e32 v37, v63, v43
	v_sub_f32_e32 v39, v63, v49
	v_sub_f32_e32 v41, v63, v53
	v_sub_f32_e32 v43, v63, v54
	v_sub_f32_e32 v49, v63, v55
	v_sub_f32_e32 v53, v63, v56
	v_sub_f32_e32 v54, v63, v57
	v_sub_f32_e32 v55, v63, v58
	v_sub_f32_e32 v56, v63, v59
	v_sub_f32_e32 v57, v63, v60
	v_sub_f32_e32 v58, v63, v61
	v_sub_f32_e32 v59, v63, v62
	v_sub_f32_e32 v60, v63, v63
	s_mov_b64 s[38:39], 0
	v_mov_b32_e32 v61, v2

.LBB0_811:
	s_andn2_saveexec_b64 s[4:5], s[4:5]
	s_nop 3
	v_mov_b32_e32 v0, 0
	v_mov_b32_e32 v1, v0
	v_mov_b32_e32 v2, v0
	v_mov_b32_e32 v3, v0
	s_or_b64 exec, exec, s[4:5]
	v_bfe_u32 v4, v0, 16, 1
	v_add3_u32 v0, v0, v4, s64
	v_bfe_u32 v4, v1, 16, 1
	v_lshrrev_b32_e32 v0, 16, v0
	v_add3_u32 v1, v1, v4, s64
	v_and_or_b32 v0, v1, s72, v0
	v_bfe_u32 v1, v2, 16, 1
	v_add3_u32 v1, v2, v1, s64
	v_bfe_u32 v2, v3, 16, 1
	v_lshrrev_b32_e32 v1, 16, v1
	v_add3_u32 v2, v3, v2, s64
	v_and_or_b32 v1, v2, s72, v1
	v_mad_u64_u32 v[2:3], s[4:5], v7, s68, v[6:7]
	s_ashr_i32 s15, s14, 31
	v_lshlrev_b32_e32 v18, 6, v30
	s_lshl_b64 s[4:5], s[14:15], 7
	v_or_b32_e32 v50, s4, v27
	v_mov_b32_e32 v51, s5
	v_ashrrev_i32_e32 v19, 31, v18
	ds_write_b64 v2, v[0:1]
	v_lshlrev_b32_e32 v16, 1, v5
	v_lshl_add_u64 v[0:1], v[50:51], 0, v[18:19]
	v_lshl_add_u64 v[52:53], s[16:17], 0, v[16:17]
	v_lshlrev_b64 v[0:1], 8, v[0:1]
	v_lshl_add_u64 v[42:43], v[52:53], 0, v[0:1]
	s_waitcnt lgkmcnt(0)
	s_barrier
	v_lshl_or_b32 v32, v29, 4, v27
	v_mad_u32_u24 v31, v32, s70, 0
	ds_read_b128 v[184:187], v102
	ds_read_b128 v[188:191], v102 offset:64
	ds_read_b128 v[192:195], v103
	ds_read_b128 v[196:199], v103 offset:64
	ds_read_b128 v[200:203], v103 offset:128
	ds_read_b128 v[204:207], v103 offset:192
	ds_read_b128 v[36:39], v101
	ds_read_b128 v[40:43], v101 offset:64
	ds_read_b128 v[44:47], v100
	ds_read_b128 v[48:51], v100 offset:64
	ds_read_b128 v[52:55], v100 offset:128
	ds_read_b128 v[56:59], v100 offset:192
	s_lshl_b32 s99, s74, 2
	s_add_u32 s100, s26, s99
	s_addc_u32 s101, s27, 0
	v_or_b32_e32 v84, v26, v18
	v_lshlrev_b32_e32 v85, 2, v84
	global_load_dwordx4 v[208:211], v85, s[100:101]
	global_load_dwordx4 v[212:215], v85, s[100:101] offset:64
	global_load_dwordx4 v[216:219], v85, s[100:101] offset:128
	global_load_dwordx4 v[220:223], v85, s[100:101] offset:192
	v_or_b32_e32 v86, s30, v32
	v_lshlrev_b32_e32 v88, 1, v84
	v_add_u32_e32 v88, s28, v88
	v_mov_b32_e32 v89, 0
	v_lshl_add_u64 v[88:89], v[88:89], 0, s[24:25]
	v_mad_u64_u32 v[88:89], vcc, v86, s2, v[88:89]
	global_load_dwordx2 v[224:225], v[88:89], off offset:3072
	global_load_dwordx2 v[226:227], v[88:89], off offset:3104
	global_load_dwordx2 v[228:229], v[88:89], off offset:3136
	global_load_dwordx2 v[230:231], v[88:89], off offset:3168
	s_add_i32 s98, s14, s22
	s_cmpk_lt_i32 s98, 0x400
	s_cselect_b32 s98, s98, s14
	s_lshr_b32 s99, s98, 7
	s_lshl_b32 s99, s99, 11
	s_lshl_b32 s100, s98, 6
	s_and_b32 s100, s100, 0x7c0
	s_or_b32 s99, s99, s100
	s_lshl_b32 s100, s98, 2
	s_and_b32 s100, s100, 0x180
	v_lshrrev_b32_e32 v176, 7, v156
	v_lshl_add_u32 v176, v176, 4, s99
	v_and_b32_e32 v178, 0x7f, v156
	v_or_b32_e32 v177, s100, v178
	v_lshlrev_b32_e32 v177, 2, v177
	global_load_dword v232, v177, s[18:19] offset:2048
	global_load_dword v233, v177, s[18:19]
	s_lshl_b32 s100, s100, 1
	v_lshl_add_u32 v178, v178, 1, s100
	v_mov_b32_e32 v179, 0
	v_lshl_add_u64 v[152:153], v[178:179], 0, s[24:25]
	v_mad_u64_u32 v[152:153], vcc, v176, s2, v[152:153]
	s_lshl_b32 s100, s98, 15
	s_add_u32 s100, s16, s100
	s_addc_u32 s101, s17, 0
	global_load_dwordx4 v[160:163], v97, s[100:101]
	s_add_u32 s100, s100, 0x2000
	s_addc_u32 s101, s101, 0
	global_load_dwordx4 v[164:167], v97, s[100:101]
	s_add_u32 s100, s100, 0x2000
	s_addc_u32 s101, s101, 0
	global_load_dwordx4 v[168:171], v97, s[100:101]
	s_add_u32 s100, s100, 0x2000
	s_addc_u32 s101, s101, 0
	global_load_dwordx4 v[172:175], v97, s[100:101]
	s_mov_b32 s100, 0x3c00
	s_mov_b32 s101, 0
	global_load_ushort v104, v[152:153], off
	global_load_ushort v105, v[152:153], off offset:1024
	global_load_ushort v106, v[152:153], off offset:2048
	v_lshl_add_u64 v[154:155], v[152:153], 0, s[100:101]
	global_load_ushort v107, v[154:155], off
	global_load_ushort v108, v[154:155], off offset:1024
	global_load_ushort v109, v[154:155], off offset:2048
	v_lshl_add_u64 v[158:159], v[154:155], 0, s[100:101]
	global_load_ushort v110, v[158:159], off
	global_load_ushort v111, v[158:159], off offset:1024
	global_load_ushort v112, v[158:159], off offset:2048
	v_lshl_add_u64 v[154:155], v[158:159], 0, s[100:101]
	global_load_ushort v113, v[154:155], off
	global_load_ushort v114, v[154:155], off offset:1024
	global_load_ushort v115, v[154:155], off offset:2048
	v_lshl_add_u64 v[158:159], v[154:155], 0, s[100:101]
	global_load_ushort v116, v[158:159], off
	global_load_ushort v117, v[158:159], off offset:1024
	global_load_ushort v118, v[158:159], off offset:2048
	v_lshl_add_u64 v[154:155], v[158:159], 0, s[100:101]
	global_load_ushort v119, v[154:155], off
	global_load_ushort v120, v[154:155], off offset:1024
	global_load_ushort v121, v[154:155], off offset:2048
	v_lshl_add_u64 v[158:159], v[154:155], 0, s[100:101]
	global_load_ushort v122, v[158:159], off
	global_load_ushort v123, v[158:159], off offset:1024
	global_load_ushort v124, v[158:159], off offset:2048
	v_lshl_add_u64 v[154:155], v[158:159], 0, s[100:101]
	global_load_ushort v125, v[154:155], off
	global_load_ushort v126, v[154:155], off offset:1024
	global_load_ushort v127, v[154:155], off offset:2048
	v_lshl_add_u64 v[158:159], v[154:155], 0, s[100:101]
	global_load_ushort v128, v[158:159], off
	global_load_ushort v129, v[158:159], off offset:1024
	global_load_ushort v130, v[158:159], off offset:2048
	v_lshl_add_u64 v[154:155], v[158:159], 0, s[100:101]
	global_load_ushort v131, v[154:155], off
	global_load_ushort v132, v[154:155], off offset:1024
	global_load_ushort v133, v[154:155], off offset:2048
	v_lshl_add_u64 v[158:159], v[154:155], 0, s[100:101]
	global_load_ushort v134, v[158:159], off
	global_load_ushort v135, v[158:159], off offset:1024
	global_load_ushort v136, v[158:159], off offset:2048
	v_lshl_add_u64 v[154:155], v[158:159], 0, s[100:101]
	global_load_ushort v137, v[154:155], off
	global_load_ushort v138, v[154:155], off offset:1024
	global_load_ushort v139, v[154:155], off offset:2048
	v_lshl_add_u64 v[158:159], v[154:155], 0, s[100:101]
	global_load_ushort v140, v[158:159], off
	global_load_ushort v141, v[158:159], off offset:1024
	global_load_ushort v142, v[158:159], off offset:2048
	v_lshl_add_u64 v[154:155], v[158:159], 0, s[100:101]
	global_load_ushort v143, v[154:155], off
	global_load_ushort v144, v[154:155], off offset:1024
	global_load_ushort v145, v[154:155], off offset:2048
	v_lshl_add_u64 v[158:159], v[154:155], 0, s[100:101]
	global_load_ushort v146, v[158:159], off
	global_load_ushort v147, v[158:159], off offset:1024
	global_load_ushort v148, v[158:159], off offset:2048
	v_lshl_add_u64 v[154:155], v[158:159], 0, s[100:101]
	global_load_ushort v149, v[154:155], off
	global_load_ushort v150, v[154:155], off offset:1024
	global_load_ushort v151, v[154:155], off offset:2048
	s_waitcnt lgkmcnt(6)
	ds_read_b128 v[60:63], v101 offset:2304
	ds_read_b128 v[64:67], v101 offset:2368
	ds_read_b128 v[68:71], v100 offset:4352
	ds_read_b128 v[72:75], v100 offset:4416
	ds_read_b128 v[76:79], v100 offset:4480
	ds_read_b128 v[80:83], v100 offset:4544
	s_waitcnt lgkmcnt(6)
	v_mfma_f32_16x16x32_bf16 v[12:15], v[36:39], v[184:187], 0
	v_mfma_f32_16x16x32_bf16 v[12:15], v[40:43], v[188:191], v[12:15]
	v_mfma_f32_16x16x32_bf16 v[12:15], v[44:47], v[192:195], v[12:15]
	v_mfma_f32_16x16x32_bf16 v[12:15], v[48:51], v[196:199], v[12:15]
	v_mfma_f32_16x16x32_bf16 v[12:15], v[52:55], v[200:203], v[12:15]
	v_mfma_f32_16x16x32_bf16 v[12:15], v[56:59], v[204:207], v[12:15]
	ds_read_b128 v[36:39], v101 offset:4608
	ds_read_b128 v[40:43], v101 offset:4672
	ds_read_b128 v[44:47], v100 offset:8704
	ds_read_b128 v[48:51], v100 offset:8768
	ds_read_b128 v[52:55], v100 offset:8832
	ds_read_b128 v[56:59], v100 offset:8896
	s_waitcnt lgkmcnt(6)
	v_mfma_f32_16x16x32_bf16 v[8:11], v[60:63], v[184:187], 0
	v_mfma_f32_16x16x32_bf16 v[8:11], v[64:67], v[188:191], v[8:11]
	v_mfma_f32_16x16x32_bf16 v[8:11], v[68:71], v[192:195], v[8:11]
	v_mfma_f32_16x16x32_bf16 v[8:11], v[72:75], v[196:199], v[8:11]
	v_mfma_f32_16x16x32_bf16 v[8:11], v[76:79], v[200:203], v[8:11]
	v_mfma_f32_16x16x32_bf16 v[8:11], v[80:83], v[204:207], v[8:11]
	ds_read_b128 v[60:63], v101 offset:6912
	ds_read_b128 v[64:67], v101 offset:6976
	ds_read_b128 v[68:71], v100 offset:13056
	ds_read_b128 v[72:75], v100 offset:13120
	ds_read_b128 v[76:79], v100 offset:13184
	ds_read_b128 v[80:83], v100 offset:13248
	s_waitcnt lgkmcnt(6)
	v_mfma_f32_16x16x32_bf16 v[4:7], v[36:39], v[184:187], 0
	v_mfma_f32_16x16x32_bf16 v[4:7], v[40:43], v[188:191], v[4:7]
	v_mfma_f32_16x16x32_bf16 v[4:7], v[44:47], v[192:195], v[4:7]
	v_mfma_f32_16x16x32_bf16 v[4:7], v[48:51], v[196:199], v[4:7]
	v_mfma_f32_16x16x32_bf16 v[4:7], v[52:55], v[200:203], v[4:7]
	v_mfma_f32_16x16x32_bf16 v[4:7], v[56:59], v[204:207], v[4:7]
	s_waitcnt lgkmcnt(0)
	v_mfma_f32_16x16x32_bf16 v[0:3], v[60:63], v[184:187], 0
	v_mfma_f32_16x16x32_bf16 v[0:3], v[64:67], v[188:191], v[0:3]
	v_mfma_f32_16x16x32_bf16 v[0:3], v[68:71], v[192:195], v[0:3]
	v_mfma_f32_16x16x32_bf16 v[0:3], v[72:75], v[196:199], v[0:3]
	v_mfma_f32_16x16x32_bf16 v[0:3], v[76:79], v[200:203], v[0:3]
	v_mfma_f32_16x16x32_bf16 v[0:3], v[80:83], v[204:207], v[0:3]
	v_mul_f32_e32 v16, v13, v13
	v_mul_f32_e32 v19, v9, v9
	v_fmac_f32_e32 v16, v12, v12
	v_fmac_f32_e32 v19, v8, v8
	v_fmac_f32_e32 v16, v14, v14
	v_fmac_f32_e32 v19, v10, v10
	v_fmac_f32_e32 v16, v15, v15
	v_fmac_f32_e32 v19, v11, v11
	v_add_f32_e32 v16, v16, v19
	v_mul_f32_e32 v19, v5, v5
	v_fmac_f32_e32 v19, v4, v4
	v_fmac_f32_e32 v19, v6, v6
	v_fmac_f32_e32 v19, v7, v7
	v_add_f32_e32 v16, v16, v19
	v_mul_f32_e32 v19, v1, v1
	v_fmac_f32_e32 v19, v0, v0
	v_fmac_f32_e32 v19, v2, v2
	v_fmac_f32_e32 v19, v3, v3
	v_add_f32_e32 v16, v16, v19
	ds_bpermute_b32 v19, v22, v16
	v_cmp_eq_u32_e32 vcc, 0, v28
	s_waitcnt lgkmcnt(0)
	v_add_f32_e32 v16, v16, v19
	ds_bpermute_b32 v19, v23, v16
	s_and_saveexec_b64 s[4:5], vcc
	s_cbranch_execz .LBB0_797
	v_lshl_add_u32 v28, v29, 7, s73
	v_lshlrev_b32_e32 v27, 3, v27
	v_lshlrev_b32_e32 v29, 2, v30
	v_add3_u32 v27, v28, v27, v29
	s_waitcnt lgkmcnt(0)
	v_add_f32_e32 v16, v16, v19
	ds_write_b32 v27, v16
	s_branch .LBB0_797

.LBB0_829:
	s_lshr_b32 s98, s94, 2
	s_and_b32 s98, s98, 1
	s_add_i32 s98, s98, 64
	s_and_b32 s99, s94, 3
	v_writelane_b32 v214, s98, 0
	v_writelane_b32 v214, s99, 1
	s_movk_i32 s98, 0x3
	v_writelane_b32 v214, s98, 2
	s_movk_i32 s98, 0x0
	v_writelane_b32 v214, s98, 3
	s_branch .Lepi_merge

.LBB0_845:
	s_lshr_b32 s98, s94, 2
	s_and_b32 s98, s98, 1
	s_add_i32 s98, s98, 64
	s_and_b32 s99, s94, 3
	v_writelane_b32 v214, s98, 0
	v_writelane_b32 v214, s99, 1
	s_movk_i32 s98, 0x13
	v_writelane_b32 v214, s98, 2
	s_movk_i32 s98, 0x5
	v_writelane_b32 v214, s98, 3
	s_branch .Lepi_merge

.LBB0_861:
	s_lshr_b32 s98, s94, 2
	s_and_b32 s98, s98, 1
	s_add_i32 s98, s98, 64
	s_and_b32 s99, s94, 3
	v_writelane_b32 v214, s98, 0
	v_writelane_b32 v214, s99, 1
	s_movk_i32 s98, 0x23
	v_writelane_b32 v214, s98, 2
	s_movk_i32 s98, 0xa
	v_writelane_b32 v214, s98, 3
	s_branch .Lepi_merge

.Lepi_p1:
	v_readlane_b32 vcc_hi, v214, 2
	s_and_b32 vcc_hi, vcc_hi, 15
	s_cmp_eq_u32 vcc_hi, 3
	s_cbranch_scc1 .Lepi_raw
	s_cmp_eq_u32 vcc_hi, 0
	s_cbranch_scc0 .Lepi_p1_nost
	global_load_dwordx2 v[164:165], v[200:201], off
	global_load_dwordx2 v[166:167], v[200:201], off offset:32
	global_load_dwordx2 v[168:169], v[200:201], off offset:256
	global_load_dwordx2 v[170:171], v[200:201], off offset:288
	s_mov_b64 s[100:101], 0x3c000
	v_lshl_add_u64 v[200:201], v[200:201], 0, s[100:101]
	global_load_dwordx2 v[172:173], v[200:201], off
	global_load_dwordx2 v[174:175], v[200:201], off offset:32
	global_load_dwordx2 v[176:177], v[200:201], off offset:256
	global_load_dwordx2 v[178:179], v[200:201], off offset:288
	s_mov_b64 s[100:101], 0x3c000
	v_lshl_add_u64 v[200:201], v[200:201], 0, s[100:101]
	global_load_dwordx2 v[180:181], v[200:201], off
	global_load_dwordx2 v[182:183], v[200:201], off offset:32
	global_load_dwordx2 v[184:185], v[200:201], off offset:256
	global_load_dwordx2 v[186:187], v[200:201], off offset:288
	s_mov_b64 s[100:101], 0x3c000
	v_lshl_add_u64 v[200:201], v[200:201], 0, s[100:101]
	global_load_dwordx2 v[188:189], v[200:201], off
	global_load_dwordx2 v[190:191], v[200:201], off offset:32
	global_load_dwordx2 v[192:193], v[200:201], off offset:256
	global_load_dwordx2 v[194:195], v[200:201], off offset:288
	s_waitcnt vmcnt(15)
	v_lshlrev_b32_e32 v206, 16, v164
	v_and_b32_e32 v207, 0xffff0000, v164
	v_lshlrev_b32_e32 v208, 16, v165
	v_and_b32_e32 v209, 0xffff0000, v165
	v_mul_f32_e32 v206, 0xbfb8aa3b, v206
	v_mul_f32_e32 v207, 0xbfb8aa3b, v207
	v_mul_f32_e32 v208, 0xbfb8aa3b, v208
	v_mul_f32_e32 v209, 0xbfb8aa3b, v209
	v_exp_f32_e32 v206, v206
	v_exp_f32_e32 v207, v207
	v_exp_f32_e32 v208, v208
	v_exp_f32_e32 v209, v209
	s_nop 0
	v_add_f32_e32 v206, 1.0, v206
	v_add_f32_e32 v207, 1.0, v207
	v_add_f32_e32 v208, 1.0, v208
	v_add_f32_e32 v209, 1.0, v209
	v_rcp_f32_e32 v206, v206
	v_rcp_f32_e32 v207, v207
	v_rcp_f32_e32 v208, v208
	v_rcp_f32_e32 v209, v209
	s_nop 0
	v_pk_mul_f32 v[124:125], v[124:125], v[206:207]
	v_pk_mul_f32 v[126:127], v[126:127], v[208:209]
	global_store_dwordx4 v[204:205], v[124:127], off
	s_mov_b64 s[100:101], 0x12c000
	v_lshl_add_u64 v[200:201], v[200:201], 0, s[100:101]
	global_load_dwordx2 v[164:165], v[200:201], off
	s_waitcnt vmcnt(16)
	v_lshlrev_b32_e32 v206, 16, v166
	v_and_b32_e32 v207, 0xffff0000, v166
	v_lshlrev_b32_e32 v208, 16, v167
	v_and_b32_e32 v209, 0xffff0000, v167
	v_mul_f32_e32 v206, 0xbfb8aa3b, v206
	v_mul_f32_e32 v207, 0xbfb8aa3b, v207
	v_mul_f32_e32 v208, 0xbfb8aa3b, v208
	v_mul_f32_e32 v209, 0xbfb8aa3b, v209
	v_exp_f32_e32 v206, v206
	v_exp_f32_e32 v207, v207
	v_exp_f32_e32 v208, v208
	v_exp_f32_e32 v209, v209
	s_nop 0
	v_add_f32_e32 v206, 1.0, v206
	v_add_f32_e32 v207, 1.0, v207
	v_add_f32_e32 v208, 1.0, v208
	v_add_f32_e32 v209, 1.0, v209
	v_rcp_f32_e32 v206, v206
	v_rcp_f32_e32 v207, v207
	v_rcp_f32_e32 v208, v208
	v_rcp_f32_e32 v209, v209
	s_nop 0
	v_pk_mul_f32 v[120:121], v[120:121], v[206:207]
	v_pk_mul_f32 v[122:123], v[122:123], v[208:209]
	global_store_dwordx4 v[204:205], v[120:123], off offset:64
	global_load_dwordx2 v[166:167], v[200:201], off offset:32
	s_waitcnt vmcnt(17)
	v_lshlrev_b32_e32 v206, 16, v168
	v_and_b32_e32 v207, 0xffff0000, v168
	v_lshlrev_b32_e32 v208, 16, v169
	v_and_b32_e32 v209, 0xffff0000, v169
	v_mul_f32_e32 v206, 0xbfb8aa3b, v206
	v_mul_f32_e32 v207, 0xbfb8aa3b, v207
	v_mul_f32_e32 v208, 0xbfb8aa3b, v208
	v_mul_f32_e32 v209, 0xbfb8aa3b, v209
	v_exp_f32_e32 v206, v206
	v_exp_f32_e32 v207, v207
	v_exp_f32_e32 v208, v208
	v_exp_f32_e32 v209, v209
	s_nop 0
	v_add_f32_e32 v206, 1.0, v206
	v_add_f32_e32 v207, 1.0, v207
	v_add_f32_e32 v208, 1.0, v208
	v_add_f32_e32 v209, 1.0, v209
	v_rcp_f32_e32 v206, v206
	v_rcp_f32_e32 v207, v207
	v_rcp_f32_e32 v208, v208
	v_rcp_f32_e32 v209, v209
	s_nop 0
	v_pk_mul_f32 v[116:117], v[116:117], v[206:207]
	v_pk_mul_f32 v[118:119], v[118:119], v[208:209]
	global_store_dwordx4 v[204:205], v[116:119], off offset:512
	global_load_dwordx2 v[168:169], v[200:201], off offset:256
	s_waitcnt vmcnt(18)
	v_lshlrev_b32_e32 v206, 16, v170
	v_and_b32_e32 v207, 0xffff0000, v170
	v_lshlrev_b32_e32 v208, 16, v171
	v_and_b32_e32 v209, 0xffff0000, v171
	v_mul_f32_e32 v206, 0xbfb8aa3b, v206
	v_mul_f32_e32 v207, 0xbfb8aa3b, v207
	v_mul_f32_e32 v208, 0xbfb8aa3b, v208
	v_mul_f32_e32 v209, 0xbfb8aa3b, v209
	v_exp_f32_e32 v206, v206
	v_exp_f32_e32 v207, v207
	v_exp_f32_e32 v208, v208
	v_exp_f32_e32 v209, v209
	s_nop 0
	v_add_f32_e32 v206, 1.0, v206
	v_add_f32_e32 v207, 1.0, v207
	v_add_f32_e32 v208, 1.0, v208
	v_add_f32_e32 v209, 1.0, v209
	v_rcp_f32_e32 v206, v206
	v_rcp_f32_e32 v207, v207
	v_rcp_f32_e32 v208, v208
	v_rcp_f32_e32 v209, v209
	s_nop 0
	v_pk_mul_f32 v[112:113], v[112:113], v[206:207]
	v_pk_mul_f32 v[114:115], v[114:115], v[208:209]
	global_store_dwordx4 v[204:205], v[112:115], off offset:576
	global_load_dwordx2 v[170:171], v[200:201], off offset:288
	s_waitcnt vmcnt(19)
	v_lshlrev_b32_e32 v206, 16, v172
	v_and_b32_e32 v207, 0xffff0000, v172
	v_lshlrev_b32_e32 v208, 16, v173
	v_and_b32_e32 v209, 0xffff0000, v173
	v_mul_f32_e32 v206, 0xbfb8aa3b, v206
	v_mul_f32_e32 v207, 0xbfb8aa3b, v207
	v_mul_f32_e32 v208, 0xbfb8aa3b, v208
	v_mul_f32_e32 v209, 0xbfb8aa3b, v209
	v_exp_f32_e32 v206, v206
	v_exp_f32_e32 v207, v207
	v_exp_f32_e32 v208, v208
	v_exp_f32_e32 v209, v209
	s_nop 0
	v_add_f32_e32 v206, 1.0, v206
	v_add_f32_e32 v207, 1.0, v207
	v_add_f32_e32 v208, 1.0, v208
	v_add_f32_e32 v209, 1.0, v209
	v_rcp_f32_e32 v206, v206
	v_rcp_f32_e32 v207, v207
	v_rcp_f32_e32 v208, v208
	v_rcp_f32_e32 v209, v209
	s_nop 0
	v_pk_mul_f32 v[108:109], v[108:109], v[206:207]
	v_pk_mul_f32 v[110:111], v[110:111], v[208:209]
	s_mov_b64 s[100:101], 0x10000
	v_lshl_add_u64 v[204:205], v[204:205], 0, s[100:101]
	global_store_dwordx4 v[204:205], v[108:111], off
	s_mov_b64 s[100:101], 0x3c000
	v_lshl_add_u64 v[200:201], v[200:201], 0, s[100:101]
	global_load_dwordx2 v[172:173], v[200:201], off
	s_waitcnt vmcnt(20)
	v_lshlrev_b32_e32 v206, 16, v174
	v_and_b32_e32 v207, 0xffff0000, v174
	v_lshlrev_b32_e32 v208, 16, v175
	v_and_b32_e32 v209, 0xffff0000, v175
	v_mul_f32_e32 v206, 0xbfb8aa3b, v206
	v_mul_f32_e32 v207, 0xbfb8aa3b, v207
	v_mul_f32_e32 v208, 0xbfb8aa3b, v208
	v_mul_f32_e32 v209, 0xbfb8aa3b, v209
	v_exp_f32_e32 v206, v206
	v_exp_f32_e32 v207, v207
	v_exp_f32_e32 v208, v208
	v_exp_f32_e32 v209, v209
	s_nop 0
	v_add_f32_e32 v206, 1.0, v206
	v_add_f32_e32 v207, 1.0, v207
	v_add_f32_e32 v208, 1.0, v208
	v_add_f32_e32 v209, 1.0, v209
	v_rcp_f32_e32 v206, v206
	v_rcp_f32_e32 v207, v207
	v_rcp_f32_e32 v208, v208
	v_rcp_f32_e32 v209, v209
	s_nop 0
	v_pk_mul_f32 v[104:105], v[104:105], v[206:207]
	v_pk_mul_f32 v[106:107], v[106:107], v[208:209]
	global_store_dwordx4 v[204:205], v[104:107], off offset:64
	global_load_dwordx2 v[174:175], v[200:201], off offset:32
	s_waitcnt vmcnt(21)
	v_lshlrev_b32_e32 v206, 16, v176
	v_and_b32_e32 v207, 0xffff0000, v176
	v_lshlrev_b32_e32 v208, 16, v177
	v_and_b32_e32 v209, 0xffff0000, v177
	v_mul_f32_e32 v206, 0xbfb8aa3b, v206
	v_mul_f32_e32 v207, 0xbfb8aa3b, v207
	v_mul_f32_e32 v208, 0xbfb8aa3b, v208
	v_mul_f32_e32 v209, 0xbfb8aa3b, v209
	v_exp_f32_e32 v206, v206
	v_exp_f32_e32 v207, v207
	v_exp_f32_e32 v208, v208
	v_exp_f32_e32 v209, v209
	s_nop 0
	v_add_f32_e32 v206, 1.0, v206
	v_add_f32_e32 v207, 1.0, v207
	v_add_f32_e32 v208, 1.0, v208
	v_add_f32_e32 v209, 1.0, v209
	v_rcp_f32_e32 v206, v206
	v_rcp_f32_e32 v207, v207
	v_rcp_f32_e32 v208, v208
	v_rcp_f32_e32 v209, v209
	s_nop 0
	v_pk_mul_f32 v[100:101], v[100:101], v[206:207]
	v_pk_mul_f32 v[102:103], v[102:103], v[208:209]
	global_store_dwordx4 v[204:205], v[100:103], off offset:512
	global_load_dwordx2 v[176:177], v[200:201], off offset:256
	s_waitcnt vmcnt(22)
	v_lshlrev_b32_e32 v206, 16, v178
	v_and_b32_e32 v207, 0xffff0000, v178
	v_lshlrev_b32_e32 v208, 16, v179
	v_and_b32_e32 v209, 0xffff0000, v179
	v_mul_f32_e32 v206, 0xbfb8aa3b, v206
	v_mul_f32_e32 v207, 0xbfb8aa3b, v207
	v_mul_f32_e32 v208, 0xbfb8aa3b, v208
	v_mul_f32_e32 v209, 0xbfb8aa3b, v209
	v_exp_f32_e32 v206, v206
	v_exp_f32_e32 v207, v207
	v_exp_f32_e32 v208, v208
	v_exp_f32_e32 v209, v209
	s_nop 0
	v_add_f32_e32 v206, 1.0, v206
	v_add_f32_e32 v207, 1.0, v207
	v_add_f32_e32 v208, 1.0, v208
	v_add_f32_e32 v209, 1.0, v209
	v_rcp_f32_e32 v206, v206
	v_rcp_f32_e32 v207, v207
	v_rcp_f32_e32 v208, v208
	v_rcp_f32_e32 v209, v209
	s_nop 0
	v_pk_mul_f32 v[96:97], v[96:97], v[206:207]
	v_pk_mul_f32 v[98:99], v[98:99], v[208:209]
	global_store_dwordx4 v[204:205], v[96:99], off offset:576
	global_load_dwordx2 v[178:179], v[200:201], off offset:288
	s_waitcnt vmcnt(23)
	v_lshlrev_b32_e32 v206, 16, v180
	v_and_b32_e32 v207, 0xffff0000, v180
	v_lshlrev_b32_e32 v208, 16, v181
	v_and_b32_e32 v209, 0xffff0000, v181
	v_mul_f32_e32 v206, 0xbfb8aa3b, v206
	v_mul_f32_e32 v207, 0xbfb8aa3b, v207
	v_mul_f32_e32 v208, 0xbfb8aa3b, v208
	v_mul_f32_e32 v209, 0xbfb8aa3b, v209
	v_exp_f32_e32 v206, v206
	v_exp_f32_e32 v207, v207
	v_exp_f32_e32 v208, v208
	v_exp_f32_e32 v209, v209
	s_nop 0
	v_add_f32_e32 v206, 1.0, v206
	v_add_f32_e32 v207, 1.0, v207
	v_add_f32_e32 v208, 1.0, v208
	v_add_f32_e32 v209, 1.0, v209
	v_rcp_f32_e32 v206, v206
	v_rcp_f32_e32 v207, v207
	v_rcp_f32_e32 v208, v208
	v_rcp_f32_e32 v209, v209
	s_nop 0
	v_pk_mul_f32 v[92:93], v[92:93], v[206:207]
	v_pk_mul_f32 v[94:95], v[94:95], v[208:209]
	s_mov_b64 s[100:101], 0x10000
	v_lshl_add_u64 v[204:205], v[204:205], 0, s[100:101]
	global_store_dwordx4 v[204:205], v[92:95], off
	s_mov_b64 s[100:101], 0x3c000
	v_lshl_add_u64 v[200:201], v[200:201], 0, s[100:101]
	global_load_dwordx2 v[180:181], v[200:201], off
	s_waitcnt vmcnt(24)
	v_lshlrev_b32_e32 v206, 16, v182
	v_and_b32_e32 v207, 0xffff0000, v182
	v_lshlrev_b32_e32 v208, 16, v183
	v_and_b32_e32 v209, 0xffff0000, v183
	v_mul_f32_e32 v206, 0xbfb8aa3b, v206
	v_mul_f32_e32 v207, 0xbfb8aa3b, v207
	v_mul_f32_e32 v208, 0xbfb8aa3b, v208
	v_mul_f32_e32 v209, 0xbfb8aa3b, v209
	v_exp_f32_e32 v206, v206
	v_exp_f32_e32 v207, v207
	v_exp_f32_e32 v208, v208
	v_exp_f32_e32 v209, v209
	s_nop 0
	v_add_f32_e32 v206, 1.0, v206
	v_add_f32_e32 v207, 1.0, v207
	v_add_f32_e32 v208, 1.0, v208
	v_add_f32_e32 v209, 1.0, v209
	v_rcp_f32_e32 v206, v206
	v_rcp_f32_e32 v207, v207
	v_rcp_f32_e32 v208, v208
	v_rcp_f32_e32 v209, v209
	s_nop 0
	v_pk_mul_f32 v[88:89], v[88:89], v[206:207]
	v_pk_mul_f32 v[90:91], v[90:91], v[208:209]
	global_store_dwordx4 v[204:205], v[88:91], off offset:64
	global_load_dwordx2 v[182:183], v[200:201], off offset:32
	s_waitcnt vmcnt(25)
	v_lshlrev_b32_e32 v206, 16, v184
	v_and_b32_e32 v207, 0xffff0000, v184
	v_lshlrev_b32_e32 v208, 16, v185
	v_and_b32_e32 v209, 0xffff0000, v185
	v_mul_f32_e32 v206, 0xbfb8aa3b, v206
	v_mul_f32_e32 v207, 0xbfb8aa3b, v207
	v_mul_f32_e32 v208, 0xbfb8aa3b, v208
	v_mul_f32_e32 v209, 0xbfb8aa3b, v209
	v_exp_f32_e32 v206, v206
	v_exp_f32_e32 v207, v207
	v_exp_f32_e32 v208, v208
	v_exp_f32_e32 v209, v209
	s_nop 0
	v_add_f32_e32 v206, 1.0, v206
	v_add_f32_e32 v207, 1.0, v207
	v_add_f32_e32 v208, 1.0, v208
	v_add_f32_e32 v209, 1.0, v209
	v_rcp_f32_e32 v206, v206
	v_rcp_f32_e32 v207, v207
	v_rcp_f32_e32 v208, v208
	v_rcp_f32_e32 v209, v209
	s_nop 0
	v_pk_mul_f32 v[84:85], v[84:85], v[206:207]
	v_pk_mul_f32 v[86:87], v[86:87], v[208:209]
	global_store_dwordx4 v[204:205], v[84:87], off offset:512
	global_load_dwordx2 v[184:185], v[200:201], off offset:256
	s_waitcnt vmcnt(26)
	v_lshlrev_b32_e32 v206, 16, v186
	v_and_b32_e32 v207, 0xffff0000, v186
	v_lshlrev_b32_e32 v208, 16, v187
	v_and_b32_e32 v209, 0xffff0000, v187
	v_mul_f32_e32 v206, 0xbfb8aa3b, v206
	v_mul_f32_e32 v207, 0xbfb8aa3b, v207
	v_mul_f32_e32 v208, 0xbfb8aa3b, v208
	v_mul_f32_e32 v209, 0xbfb8aa3b, v209
	v_exp_f32_e32 v206, v206
	v_exp_f32_e32 v207, v207
	v_exp_f32_e32 v208, v208
	v_exp_f32_e32 v209, v209
	s_nop 0
	v_add_f32_e32 v206, 1.0, v206
	v_add_f32_e32 v207, 1.0, v207
	v_add_f32_e32 v208, 1.0, v208
	v_add_f32_e32 v209, 1.0, v209
	v_rcp_f32_e32 v206, v206
	v_rcp_f32_e32 v207, v207
	v_rcp_f32_e32 v208, v208
	v_rcp_f32_e32 v209, v209
	s_nop 0
	v_pk_mul_f32 v[80:81], v[80:81], v[206:207]
	v_pk_mul_f32 v[82:83], v[82:83], v[208:209]
	global_store_dwordx4 v[204:205], v[80:83], off offset:576
	global_load_dwordx2 v[186:187], v[200:201], off offset:288
	s_waitcnt vmcnt(27)
	v_lshlrev_b32_e32 v206, 16, v188
	v_and_b32_e32 v207, 0xffff0000, v188
	v_lshlrev_b32_e32 v208, 16, v189
	v_and_b32_e32 v209, 0xffff0000, v189
	v_mul_f32_e32 v206, 0xbfb8aa3b, v206
	v_mul_f32_e32 v207, 0xbfb8aa3b, v207
	v_mul_f32_e32 v208, 0xbfb8aa3b, v208
	v_mul_f32_e32 v209, 0xbfb8aa3b, v209
	v_exp_f32_e32 v206, v206
	v_exp_f32_e32 v207, v207
	v_exp_f32_e32 v208, v208
	v_exp_f32_e32 v209, v209
	s_nop 0
	v_add_f32_e32 v206, 1.0, v206
	v_add_f32_e32 v207, 1.0, v207
	v_add_f32_e32 v208, 1.0, v208
	v_add_f32_e32 v209, 1.0, v209
	v_rcp_f32_e32 v206, v206
	v_rcp_f32_e32 v207, v207
	v_rcp_f32_e32 v208, v208
	v_rcp_f32_e32 v209, v209
	s_nop 0
	v_pk_mul_f32 v[76:77], v[76:77], v[206:207]
	v_pk_mul_f32 v[78:79], v[78:79], v[208:209]
	s_mov_b64 s[100:101], 0x10000
	v_lshl_add_u64 v[204:205], v[204:205], 0, s[100:101]
	global_store_dwordx4 v[204:205], v[76:79], off
	s_mov_b64 s[100:101], 0x3c000
	v_lshl_add_u64 v[200:201], v[200:201], 0, s[100:101]
	global_load_dwordx2 v[188:189], v[200:201], off
	s_waitcnt vmcnt(28)
	v_lshlrev_b32_e32 v206, 16, v190
	v_and_b32_e32 v207, 0xffff0000, v190
	v_lshlrev_b32_e32 v208, 16, v191
	v_and_b32_e32 v209, 0xffff0000, v191
	v_mul_f32_e32 v206, 0xbfb8aa3b, v206
	v_mul_f32_e32 v207, 0xbfb8aa3b, v207
	v_mul_f32_e32 v208, 0xbfb8aa3b, v208
	v_mul_f32_e32 v209, 0xbfb8aa3b, v209
	v_exp_f32_e32 v206, v206
	v_exp_f32_e32 v207, v207
	v_exp_f32_e32 v208, v208
	v_exp_f32_e32 v209, v209
	s_nop 0
	v_add_f32_e32 v206, 1.0, v206
	v_add_f32_e32 v207, 1.0, v207
	v_add_f32_e32 v208, 1.0, v208
	v_add_f32_e32 v209, 1.0, v209
	v_rcp_f32_e32 v206, v206
	v_rcp_f32_e32 v207, v207
	v_rcp_f32_e32 v208, v208
	v_rcp_f32_e32 v209, v209
	s_nop 0
	v_pk_mul_f32 v[72:73], v[72:73], v[206:207]
	v_pk_mul_f32 v[74:75], v[74:75], v[208:209]
	global_store_dwordx4 v[204:205], v[72:75], off offset:64
	global_load_dwordx2 v[190:191], v[200:201], off offset:32
	s_waitcnt vmcnt(29)
	v_lshlrev_b32_e32 v206, 16, v192
	v_and_b32_e32 v207, 0xffff0000, v192
	v_lshlrev_b32_e32 v208, 16, v193
	v_and_b32_e32 v209, 0xffff0000, v193
	v_mul_f32_e32 v206, 0xbfb8aa3b, v206
	v_mul_f32_e32 v207, 0xbfb8aa3b, v207
	v_mul_f32_e32 v208, 0xbfb8aa3b, v208
	v_mul_f32_e32 v209, 0xbfb8aa3b, v209
	v_exp_f32_e32 v206, v206
	v_exp_f32_e32 v207, v207
	v_exp_f32_e32 v208, v208
	v_exp_f32_e32 v209, v209
	s_nop 0
	v_add_f32_e32 v206, 1.0, v206
	v_add_f32_e32 v207, 1.0, v207
	v_add_f32_e32 v208, 1.0, v208
	v_add_f32_e32 v209, 1.0, v209
	v_rcp_f32_e32 v206, v206
	v_rcp_f32_e32 v207, v207
	v_rcp_f32_e32 v208, v208
	v_rcp_f32_e32 v209, v209
	s_nop 0
	v_pk_mul_f32 v[68:69], v[68:69], v[206:207]
	v_pk_mul_f32 v[70:71], v[70:71], v[208:209]
	global_store_dwordx4 v[204:205], v[68:71], off offset:512
	global_load_dwordx2 v[192:193], v[200:201], off offset:256
	s_waitcnt vmcnt(30)
	v_lshlrev_b32_e32 v206, 16, v194
	v_and_b32_e32 v207, 0xffff0000, v194
	v_lshlrev_b32_e32 v208, 16, v195
	v_and_b32_e32 v209, 0xffff0000, v195
	v_mul_f32_e32 v206, 0xbfb8aa3b, v206
	v_mul_f32_e32 v207, 0xbfb8aa3b, v207
	v_mul_f32_e32 v208, 0xbfb8aa3b, v208
	v_mul_f32_e32 v209, 0xbfb8aa3b, v209
	v_exp_f32_e32 v206, v206
	v_exp_f32_e32 v207, v207
	v_exp_f32_e32 v208, v208
	v_exp_f32_e32 v209, v209
	s_nop 0
	v_add_f32_e32 v206, 1.0, v206
	v_add_f32_e32 v207, 1.0, v207
	v_add_f32_e32 v208, 1.0, v208
	v_add_f32_e32 v209, 1.0, v209
	v_rcp_f32_e32 v206, v206
	v_rcp_f32_e32 v207, v207
	v_rcp_f32_e32 v208, v208
	v_rcp_f32_e32 v209, v209
	s_nop 0
	v_pk_mul_f32 v[64:65], v[64:65], v[206:207]
	v_pk_mul_f32 v[66:67], v[66:67], v[208:209]
	global_store_dwordx4 v[204:205], v[64:67], off offset:576
	global_load_dwordx2 v[194:195], v[200:201], off offset:288
	s_waitcnt vmcnt(30)
	v_lshlrev_b32_e32 v206, 16, v164
	v_and_b32_e32 v207, 0xffff0000, v164
	v_lshlrev_b32_e32 v208, 16, v165
	v_and_b32_e32 v209, 0xffff0000, v165
	v_mul_f32_e32 v206, 0xbfb8aa3b, v206
	v_mul_f32_e32 v207, 0xbfb8aa3b, v207
	v_mul_f32_e32 v208, 0xbfb8aa3b, v208
	v_mul_f32_e32 v209, 0xbfb8aa3b, v209
	v_exp_f32_e32 v206, v206
	v_exp_f32_e32 v207, v207
	v_exp_f32_e32 v208, v208
	v_exp_f32_e32 v209, v209
	s_nop 0
	v_add_f32_e32 v206, 1.0, v206
	v_add_f32_e32 v207, 1.0, v207
	v_add_f32_e32 v208, 1.0, v208
	v_add_f32_e32 v209, 1.0, v209
	v_rcp_f32_e32 v206, v206
	v_rcp_f32_e32 v207, v207
	v_rcp_f32_e32 v208, v208
	v_rcp_f32_e32 v209, v209
	s_nop 0
	v_pk_mul_f32 v[60:61], v[60:61], v[206:207]
	v_pk_mul_f32 v[62:63], v[62:63], v[208:209]
	s_mov_b64 s[100:101], 0x50000
	v_lshl_add_u64 v[204:205], v[204:205], 0, s[100:101]
	global_store_dwordx4 v[204:205], v[60:63], off
	s_waitcnt vmcnt(29)
	v_lshlrev_b32_e32 v206, 16, v166
	v_and_b32_e32 v207, 0xffff0000, v166
	v_lshlrev_b32_e32 v208, 16, v167
	v_and_b32_e32 v209, 0xffff0000, v167
	v_mul_f32_e32 v206, 0xbfb8aa3b, v206
	v_mul_f32_e32 v207, 0xbfb8aa3b, v207
	v_mul_f32_e32 v208, 0xbfb8aa3b, v208
	v_mul_f32_e32 v209, 0xbfb8aa3b, v209
	v_exp_f32_e32 v206, v206
	v_exp_f32_e32 v207, v207
	v_exp_f32_e32 v208, v208
	v_exp_f32_e32 v209, v209
	s_nop 0
	v_add_f32_e32 v206, 1.0, v206
	v_add_f32_e32 v207, 1.0, v207
	v_add_f32_e32 v208, 1.0, v208
	v_add_f32_e32 v209, 1.0, v209
	v_rcp_f32_e32 v206, v206
	v_rcp_f32_e32 v207, v207
	v_rcp_f32_e32 v208, v208
	v_rcp_f32_e32 v209, v209
	s_nop 0
	v_pk_mul_f32 v[56:57], v[56:57], v[206:207]
	v_pk_mul_f32 v[58:59], v[58:59], v[208:209]
	global_store_dwordx4 v[204:205], v[56:59], off offset:64
	s_waitcnt vmcnt(28)
	v_lshlrev_b32_e32 v206, 16, v168
	v_and_b32_e32 v207, 0xffff0000, v168
	v_lshlrev_b32_e32 v208, 16, v169
	v_and_b32_e32 v209, 0xffff0000, v169
	v_mul_f32_e32 v206, 0xbfb8aa3b, v206
	v_mul_f32_e32 v207, 0xbfb8aa3b, v207
	v_mul_f32_e32 v208, 0xbfb8aa3b, v208
	v_mul_f32_e32 v209, 0xbfb8aa3b, v209
	v_exp_f32_e32 v206, v206
	v_exp_f32_e32 v207, v207
	v_exp_f32_e32 v208, v208
	v_exp_f32_e32 v209, v209
	s_nop 0
	v_add_f32_e32 v206, 1.0, v206
	v_add_f32_e32 v207, 1.0, v207
	v_add_f32_e32 v208, 1.0, v208
	v_add_f32_e32 v209, 1.0, v209
	v_rcp_f32_e32 v206, v206
	v_rcp_f32_e32 v207, v207
	v_rcp_f32_e32 v208, v208
	v_rcp_f32_e32 v209, v209
	s_nop 0
	v_pk_mul_f32 v[52:53], v[52:53], v[206:207]
	v_pk_mul_f32 v[54:55], v[54:55], v[208:209]
	global_store_dwordx4 v[204:205], v[52:55], off offset:512
	s_waitcnt vmcnt(27)
	v_lshlrev_b32_e32 v206, 16, v170
	v_and_b32_e32 v207, 0xffff0000, v170
	v_lshlrev_b32_e32 v208, 16, v171
	v_and_b32_e32 v209, 0xffff0000, v171
	v_mul_f32_e32 v206, 0xbfb8aa3b, v206
	v_mul_f32_e32 v207, 0xbfb8aa3b, v207
	v_mul_f32_e32 v208, 0xbfb8aa3b, v208
	v_mul_f32_e32 v209, 0xbfb8aa3b, v209
	v_exp_f32_e32 v206, v206
	v_exp_f32_e32 v207, v207
	v_exp_f32_e32 v208, v208
	v_exp_f32_e32 v209, v209
	s_nop 0
	v_add_f32_e32 v206, 1.0, v206
	v_add_f32_e32 v207, 1.0, v207
	v_add_f32_e32 v208, 1.0, v208
	v_add_f32_e32 v209, 1.0, v209
	v_rcp_f32_e32 v206, v206
	v_rcp_f32_e32 v207, v207
	v_rcp_f32_e32 v208, v208
	v_rcp_f32_e32 v209, v209
	s_nop 0
	v_pk_mul_f32 v[48:49], v[48:49], v[206:207]
	v_pk_mul_f32 v[50:51], v[50:51], v[208:209]
	global_store_dwordx4 v[204:205], v[48:51], off offset:576
	s_waitcnt vmcnt(26)
	v_lshlrev_b32_e32 v206, 16, v172
	v_and_b32_e32 v207, 0xffff0000, v172
	v_lshlrev_b32_e32 v208, 16, v173
	v_and_b32_e32 v209, 0xffff0000, v173
	v_mul_f32_e32 v206, 0xbfb8aa3b, v206
	v_mul_f32_e32 v207, 0xbfb8aa3b, v207
	v_mul_f32_e32 v208, 0xbfb8aa3b, v208
	v_mul_f32_e32 v209, 0xbfb8aa3b, v209
	v_exp_f32_e32 v206, v206
	v_exp_f32_e32 v207, v207
	v_exp_f32_e32 v208, v208
	v_exp_f32_e32 v209, v209
	s_nop 0
	v_add_f32_e32 v206, 1.0, v206
	v_add_f32_e32 v207, 1.0, v207
	v_add_f32_e32 v208, 1.0, v208
	v_add_f32_e32 v209, 1.0, v209
	v_rcp_f32_e32 v206, v206
	v_rcp_f32_e32 v207, v207
	v_rcp_f32_e32 v208, v208
	v_rcp_f32_e32 v209, v209
	s_nop 0
	v_pk_mul_f32 v[44:45], v[44:45], v[206:207]
	v_pk_mul_f32 v[46:47], v[46:47], v[208:209]
	s_mov_b64 s[100:101], 0x10000
	v_lshl_add_u64 v[204:205], v[204:205], 0, s[100:101]
	global_store_dwordx4 v[204:205], v[44:47], off
	s_waitcnt vmcnt(25)
	v_lshlrev_b32_e32 v206, 16, v174
	v_and_b32_e32 v207, 0xffff0000, v174
	v_lshlrev_b32_e32 v208, 16, v175
	v_and_b32_e32 v209, 0xffff0000, v175
	v_mul_f32_e32 v206, 0xbfb8aa3b, v206
	v_mul_f32_e32 v207, 0xbfb8aa3b, v207
	v_mul_f32_e32 v208, 0xbfb8aa3b, v208
	v_mul_f32_e32 v209, 0xbfb8aa3b, v209
	v_exp_f32_e32 v206, v206
	v_exp_f32_e32 v207, v207
	v_exp_f32_e32 v208, v208
	v_exp_f32_e32 v209, v209
	s_nop 0
	v_add_f32_e32 v206, 1.0, v206
	v_add_f32_e32 v207, 1.0, v207
	v_add_f32_e32 v208, 1.0, v208
	v_add_f32_e32 v209, 1.0, v209
	v_rcp_f32_e32 v206, v206
	v_rcp_f32_e32 v207, v207
	v_rcp_f32_e32 v208, v208
	v_rcp_f32_e32 v209, v209
	s_nop 0
	v_pk_mul_f32 v[40:41], v[40:41], v[206:207]
	v_pk_mul_f32 v[42:43], v[42:43], v[208:209]
	global_store_dwordx4 v[204:205], v[40:43], off offset:64
	s_waitcnt vmcnt(24)
	v_lshlrev_b32_e32 v206, 16, v176
	v_and_b32_e32 v207, 0xffff0000, v176
	v_lshlrev_b32_e32 v208, 16, v177
	v_and_b32_e32 v209, 0xffff0000, v177
	v_mul_f32_e32 v206, 0xbfb8aa3b, v206
	v_mul_f32_e32 v207, 0xbfb8aa3b, v207
	v_mul_f32_e32 v208, 0xbfb8aa3b, v208
	v_mul_f32_e32 v209, 0xbfb8aa3b, v209
	v_exp_f32_e32 v206, v206
	v_exp_f32_e32 v207, v207
	v_exp_f32_e32 v208, v208
	v_exp_f32_e32 v209, v209
	s_nop 0
	v_add_f32_e32 v206, 1.0, v206
	v_add_f32_e32 v207, 1.0, v207
	v_add_f32_e32 v208, 1.0, v208
	v_add_f32_e32 v209, 1.0, v209
	v_rcp_f32_e32 v206, v206
	v_rcp_f32_e32 v207, v207
	v_rcp_f32_e32 v208, v208
	v_rcp_f32_e32 v209, v209
	s_nop 0
	v_pk_mul_f32 v[36:37], v[36:37], v[206:207]
	v_pk_mul_f32 v[38:39], v[38:39], v[208:209]
	global_store_dwordx4 v[204:205], v[36:39], off offset:512
	s_waitcnt vmcnt(23)
	v_lshlrev_b32_e32 v206, 16, v178
	v_and_b32_e32 v207, 0xffff0000, v178
	v_lshlrev_b32_e32 v208, 16, v179
	v_and_b32_e32 v209, 0xffff0000, v179
	v_mul_f32_e32 v206, 0xbfb8aa3b, v206
	v_mul_f32_e32 v207, 0xbfb8aa3b, v207
	v_mul_f32_e32 v208, 0xbfb8aa3b, v208
	v_mul_f32_e32 v209, 0xbfb8aa3b, v209
	v_exp_f32_e32 v206, v206
	v_exp_f32_e32 v207, v207
	v_exp_f32_e32 v208, v208
	v_exp_f32_e32 v209, v209
	s_nop 0
	v_add_f32_e32 v206, 1.0, v206
	v_add_f32_e32 v207, 1.0, v207
	v_add_f32_e32 v208, 1.0, v208
	v_add_f32_e32 v209, 1.0, v209
	v_rcp_f32_e32 v206, v206
	v_rcp_f32_e32 v207, v207
	v_rcp_f32_e32 v208, v208
	v_rcp_f32_e32 v209, v209
	s_nop 0
	v_pk_mul_f32 v[32:33], v[32:33], v[206:207]
	v_pk_mul_f32 v[34:35], v[34:35], v[208:209]
	global_store_dwordx4 v[204:205], v[32:35], off offset:576
	s_waitcnt vmcnt(22)
	v_lshlrev_b32_e32 v206, 16, v180
	v_and_b32_e32 v207, 0xffff0000, v180
	v_lshlrev_b32_e32 v208, 16, v181
	v_and_b32_e32 v209, 0xffff0000, v181
	v_mul_f32_e32 v206, 0xbfb8aa3b, v206
	v_mul_f32_e32 v207, 0xbfb8aa3b, v207
	v_mul_f32_e32 v208, 0xbfb8aa3b, v208
	v_mul_f32_e32 v209, 0xbfb8aa3b, v209
	v_exp_f32_e32 v206, v206
	v_exp_f32_e32 v207, v207
	v_exp_f32_e32 v208, v208
	v_exp_f32_e32 v209, v209
	s_nop 0
	v_add_f32_e32 v206, 1.0, v206
	v_add_f32_e32 v207, 1.0, v207
	v_add_f32_e32 v208, 1.0, v208
	v_add_f32_e32 v209, 1.0, v209
	v_rcp_f32_e32 v206, v206
	v_rcp_f32_e32 v207, v207
	v_rcp_f32_e32 v208, v208
	v_rcp_f32_e32 v209, v209
	s_nop 0
	v_pk_mul_f32 v[28:29], v[28:29], v[206:207]
	v_pk_mul_f32 v[30:31], v[30:31], v[208:209]
	s_mov_b64 s[100:101], 0x10000
	v_lshl_add_u64 v[204:205], v[204:205], 0, s[100:101]
	global_store_dwordx4 v[204:205], v[28:31], off
	s_waitcnt vmcnt(21)
	v_lshlrev_b32_e32 v206, 16, v182
	v_and_b32_e32 v207, 0xffff0000, v182
	v_lshlrev_b32_e32 v208, 16, v183
	v_and_b32_e32 v209, 0xffff0000, v183
	v_mul_f32_e32 v206, 0xbfb8aa3b, v206
	v_mul_f32_e32 v207, 0xbfb8aa3b, v207
	v_mul_f32_e32 v208, 0xbfb8aa3b, v208
	v_mul_f32_e32 v209, 0xbfb8aa3b, v209
	v_exp_f32_e32 v206, v206
	v_exp_f32_e32 v207, v207
	v_exp_f32_e32 v208, v208
	v_exp_f32_e32 v209, v209
	s_nop 0
	v_add_f32_e32 v206, 1.0, v206
	v_add_f32_e32 v207, 1.0, v207
	v_add_f32_e32 v208, 1.0, v208
	v_add_f32_e32 v209, 1.0, v209
	v_rcp_f32_e32 v206, v206
	v_rcp_f32_e32 v207, v207
	v_rcp_f32_e32 v208, v208
	v_rcp_f32_e32 v209, v209
	s_nop 0
	v_pk_mul_f32 v[24:25], v[24:25], v[206:207]
	v_pk_mul_f32 v[26:27], v[26:27], v[208:209]
	global_store_dwordx4 v[204:205], v[24:27], off offset:64
	s_waitcnt vmcnt(20)
	v_lshlrev_b32_e32 v206, 16, v184
	v_and_b32_e32 v207, 0xffff0000, v184
	v_lshlrev_b32_e32 v208, 16, v185
	v_and_b32_e32 v209, 0xffff0000, v185
	v_mul_f32_e32 v206, 0xbfb8aa3b, v206
	v_mul_f32_e32 v207, 0xbfb8aa3b, v207
	v_mul_f32_e32 v208, 0xbfb8aa3b, v208
	v_mul_f32_e32 v209, 0xbfb8aa3b, v209
	v_exp_f32_e32 v206, v206
	v_exp_f32_e32 v207, v207
	v_exp_f32_e32 v208, v208
	v_exp_f32_e32 v209, v209
	s_nop 0
	v_add_f32_e32 v206, 1.0, v206
	v_add_f32_e32 v207, 1.0, v207
	v_add_f32_e32 v208, 1.0, v208
	v_add_f32_e32 v209, 1.0, v209
	v_rcp_f32_e32 v206, v206
	v_rcp_f32_e32 v207, v207
	v_rcp_f32_e32 v208, v208
	v_rcp_f32_e32 v209, v209
	s_nop 0
	v_pk_mul_f32 v[20:21], v[20:21], v[206:207]
	v_pk_mul_f32 v[22:23], v[22:23], v[208:209]
	global_store_dwordx4 v[204:205], v[20:23], off offset:512
	s_waitcnt vmcnt(19)
	v_lshlrev_b32_e32 v206, 16, v186
	v_and_b32_e32 v207, 0xffff0000, v186
	v_lshlrev_b32_e32 v208, 16, v187
	v_and_b32_e32 v209, 0xffff0000, v187
	v_mul_f32_e32 v206, 0xbfb8aa3b, v206
	v_mul_f32_e32 v207, 0xbfb8aa3b, v207
	v_mul_f32_e32 v208, 0xbfb8aa3b, v208
	v_mul_f32_e32 v209, 0xbfb8aa3b, v209
	v_exp_f32_e32 v206, v206
	v_exp_f32_e32 v207, v207
	v_exp_f32_e32 v208, v208
	v_exp_f32_e32 v209, v209
	s_nop 0
	v_add_f32_e32 v206, 1.0, v206
	v_add_f32_e32 v207, 1.0, v207
	v_add_f32_e32 v208, 1.0, v208
	v_add_f32_e32 v209, 1.0, v209
	v_rcp_f32_e32 v206, v206
	v_rcp_f32_e32 v207, v207
	v_rcp_f32_e32 v208, v208
	v_rcp_f32_e32 v209, v209
	s_nop 0
	v_pk_mul_f32 v[16:17], v[16:17], v[206:207]
	v_pk_mul_f32 v[18:19], v[18:19], v[208:209]
	global_store_dwordx4 v[204:205], v[16:19], off offset:576
	s_waitcnt vmcnt(18)
	v_lshlrev_b32_e32 v206, 16, v188
	v_and_b32_e32 v207, 0xffff0000, v188
	v_lshlrev_b32_e32 v208, 16, v189
	v_and_b32_e32 v209, 0xffff0000, v189
	v_mul_f32_e32 v206, 0xbfb8aa3b, v206
	v_mul_f32_e32 v207, 0xbfb8aa3b, v207
	v_mul_f32_e32 v208, 0xbfb8aa3b, v208
	v_mul_f32_e32 v209, 0xbfb8aa3b, v209
	v_exp_f32_e32 v206, v206
	v_exp_f32_e32 v207, v207
	v_exp_f32_e32 v208, v208
	v_exp_f32_e32 v209, v209
	s_nop 0
	v_add_f32_e32 v206, 1.0, v206
	v_add_f32_e32 v207, 1.0, v207
	v_add_f32_e32 v208, 1.0, v208
	v_add_f32_e32 v209, 1.0, v209
	v_rcp_f32_e32 v206, v206
	v_rcp_f32_e32 v207, v207
	v_rcp_f32_e32 v208, v208
	v_rcp_f32_e32 v209, v209
	s_nop 0
	v_pk_mul_f32 v[12:13], v[12:13], v[206:207]
	v_pk_mul_f32 v[14:15], v[14:15], v[208:209]
	s_mov_b64 s[100:101], 0x10000
	v_lshl_add_u64 v[204:205], v[204:205], 0, s[100:101]
	global_store_dwordx4 v[204:205], v[12:15], off
	s_waitcnt vmcnt(17)
	v_lshlrev_b32_e32 v206, 16, v190
	v_and_b32_e32 v207, 0xffff0000, v190
	v_lshlrev_b32_e32 v208, 16, v191
	v_and_b32_e32 v209, 0xffff0000, v191
	v_mul_f32_e32 v206, 0xbfb8aa3b, v206
	v_mul_f32_e32 v207, 0xbfb8aa3b, v207
	v_mul_f32_e32 v208, 0xbfb8aa3b, v208
	v_mul_f32_e32 v209, 0xbfb8aa3b, v209
	v_exp_f32_e32 v206, v206
	v_exp_f32_e32 v207, v207
	v_exp_f32_e32 v208, v208
	v_exp_f32_e32 v209, v209
	s_nop 0
	v_add_f32_e32 v206, 1.0, v206
	v_add_f32_e32 v207, 1.0, v207
	v_add_f32_e32 v208, 1.0, v208
	v_add_f32_e32 v209, 1.0, v209
	v_rcp_f32_e32 v206, v206
	v_rcp_f32_e32 v207, v207
	v_rcp_f32_e32 v208, v208
	v_rcp_f32_e32 v209, v209
	s_nop 0
	v_pk_mul_f32 v[8:9], v[8:9], v[206:207]
	v_pk_mul_f32 v[10:11], v[10:11], v[208:209]
	global_store_dwordx4 v[204:205], v[8:11], off offset:64
	s_waitcnt vmcnt(16)
	v_lshlrev_b32_e32 v206, 16, v192
	v_and_b32_e32 v207, 0xffff0000, v192
	v_lshlrev_b32_e32 v208, 16, v193
	v_and_b32_e32 v209, 0xffff0000, v193
	v_mul_f32_e32 v206, 0xbfb8aa3b, v206
	v_mul_f32_e32 v207, 0xbfb8aa3b, v207
	v_mul_f32_e32 v208, 0xbfb8aa3b, v208
	v_mul_f32_e32 v209, 0xbfb8aa3b, v209
	v_exp_f32_e32 v206, v206
	v_exp_f32_e32 v207, v207
	v_exp_f32_e32 v208, v208
	v_exp_f32_e32 v209, v209
	s_nop 0
	v_add_f32_e32 v206, 1.0, v206
	v_add_f32_e32 v207, 1.0, v207
	v_add_f32_e32 v208, 1.0, v208
	v_add_f32_e32 v209, 1.0, v209
	v_rcp_f32_e32 v206, v206
	v_rcp_f32_e32 v207, v207
	v_rcp_f32_e32 v208, v208
	v_rcp_f32_e32 v209, v209
	s_nop 0
	v_pk_mul_f32 v[4:5], v[4:5], v[206:207]
	v_pk_mul_f32 v[6:7], v[6:7], v[208:209]
	global_store_dwordx4 v[204:205], v[4:7], off offset:512
	s_waitcnt vmcnt(15)
	v_lshlrev_b32_e32 v206, 16, v194
	v_and_b32_e32 v207, 0xffff0000, v194
	v_lshlrev_b32_e32 v208, 16, v195
	v_and_b32_e32 v209, 0xffff0000, v195
	v_mul_f32_e32 v206, 0xbfb8aa3b, v206
	v_mul_f32_e32 v207, 0xbfb8aa3b, v207
	v_mul_f32_e32 v208, 0xbfb8aa3b, v208
	v_mul_f32_e32 v209, 0xbfb8aa3b, v209
	v_exp_f32_e32 v206, v206
	v_exp_f32_e32 v207, v207
	v_exp_f32_e32 v208, v208
	v_exp_f32_e32 v209, v209
	s_nop 0
	v_add_f32_e32 v206, 1.0, v206
	v_add_f32_e32 v207, 1.0, v207
	v_add_f32_e32 v208, 1.0, v208
	v_add_f32_e32 v209, 1.0, v209
	v_rcp_f32_e32 v206, v206
	v_rcp_f32_e32 v207, v207
	v_rcp_f32_e32 v208, v208
	v_rcp_f32_e32 v209, v209
	s_nop 0
	v_pk_mul_f32 v[0:1], v[0:1], v[206:207]
	v_pk_mul_f32 v[2:3], v[2:3], v[208:209]
	global_store_dwordx4 v[204:205], v[0:3], off offset:576
	s_branch .Lepi_done
.Lepi_raw:
	global_store_dwordx4 v[204:205], v[124:127], off
	global_store_dwordx4 v[204:205], v[120:123], off offset:64
	global_store_dwordx4 v[204:205], v[116:119], off offset:512
	global_store_dwordx4 v[204:205], v[112:115], off offset:576
	s_mov_b64 s[100:101], 0x10000
	v_lshl_add_u64 v[204:205], v[204:205], 0, s[100:101]
	global_store_dwordx4 v[204:205], v[108:111], off
	global_store_dwordx4 v[204:205], v[104:107], off offset:64
	global_store_dwordx4 v[204:205], v[100:103], off offset:512
	global_store_dwordx4 v[204:205], v[96:99], off offset:576
	s_mov_b64 s[100:101], 0x10000
	v_lshl_add_u64 v[204:205], v[204:205], 0, s[100:101]
	global_store_dwordx4 v[204:205], v[92:95], off
	global_store_dwordx4 v[204:205], v[88:91], off offset:64
	global_store_dwordx4 v[204:205], v[84:87], off offset:512
	global_store_dwordx4 v[204:205], v[80:83], off offset:576
	s_mov_b64 s[100:101], 0x10000
	v_lshl_add_u64 v[204:205], v[204:205], 0, s[100:101]
	global_store_dwordx4 v[204:205], v[76:79], off
	global_store_dwordx4 v[204:205], v[72:75], off offset:64
	global_store_dwordx4 v[204:205], v[68:71], off offset:512
	global_store_dwordx4 v[204:205], v[64:67], off offset:576
	s_mov_b64 s[100:101], 0x50000
	v_lshl_add_u64 v[204:205], v[204:205], 0, s[100:101]
	global_store_dwordx4 v[204:205], v[60:63], off
	global_store_dwordx4 v[204:205], v[56:59], off offset:64
	global_store_dwordx4 v[204:205], v[52:55], off offset:512
	global_store_dwordx4 v[204:205], v[48:51], off offset:576
	s_mov_b64 s[100:101], 0x10000
	v_lshl_add_u64 v[204:205], v[204:205], 0, s[100:101]
	global_store_dwordx4 v[204:205], v[44:47], off
	global_store_dwordx4 v[204:205], v[40:43], off offset:64
	global_store_dwordx4 v[204:205], v[36:39], off offset:512
	global_store_dwordx4 v[204:205], v[32:35], off offset:576
	s_mov_b64 s[100:101], 0x10000
	v_lshl_add_u64 v[204:205], v[204:205], 0, s[100:101]
	global_store_dwordx4 v[204:205], v[28:31], off
	global_store_dwordx4 v[204:205], v[24:27], off offset:64
	global_store_dwordx4 v[204:205], v[20:23], off offset:512
	global_store_dwordx4 v[204:205], v[16:19], off offset:576
	s_mov_b64 s[100:101], 0x10000
	v_lshl_add_u64 v[204:205], v[204:205], 0, s[100:101]
	global_store_dwordx4 v[204:205], v[12:15], off
	global_store_dwordx4 v[204:205], v[8:11], off offset:64
	global_store_dwordx4 v[204:205], v[4:7], off offset:512
	global_store_dwordx4 v[204:205], v[0:3], off offset:576
	s_branch .Lepi_done

.LBB0_921:
	s_load_dwordx2 s[98:99], s[0:1], 0xd8
	v_lshrrev_b32_e32 v0, 8, v156
	v_lshl_add_u32 v0, s94, 1, v0
	v_and_b32_e32 v1, 0xff, v156
	v_lshlrev_b32_e32 v2, 12, v0
	v_lshl_add_u32 v2, v1, 4, v2
	v_lshlrev_b32_e32 v3, 11, v0
	v_lshl_add_u32 v3, v1, 3, v3
	v_mul_u32_u24_e32 v28, 0x3c00, v0
	v_lshl_add_u32 v28, v1, 3, v28
	v_cmp_gt_u32_e32 vcc, 0x200, v0
	s_and_saveexec_b64 s[100:101], vcc
	s_cbranch_execz .Lcomb_done
	s_waitcnt lgkmcnt(0)
	s_add_u32 s98, s98, 0x4000000
	s_addc_u32 s99, s99, 0
	global_load_dwordx4 v[4:7], v2, s[98:99]
	s_add_u32 s98, s40, 0x1830000
	s_addc_u32 s99, s41, 0
	global_load_dwordx4 v[8:11], v2, s[98:99]
	s_add_u32 s98, s40, 0x1a30000
	s_addc_u32 s99, s41, 0
	global_load_dwordx4 v[12:15], v2, s[98:99]
	s_add_u32 s98, s40, 0x11032400
	s_addc_u32 s99, s41, 0
	global_load_dwordx2 v[16:17], v28, s[98:99]
	global_load_dwordx2 v[18:19], v28, s[98:99] offset:2048
	s_add_u32 s98, s98, 0x1000
	s_addc_u32 s99, s99, 0
	global_load_dwordx2 v[20:21], v28, s[98:99]
	s_add_u32 s98, s40, 0x15034000
	s_addc_u32 s99, s41, 0
	s_waitcnt vmcnt(0)
	v_lshlrev_b32_e32 v24, 16, v16
	v_and_b32_e32 v25, 0xffff0000, v16
	v_lshlrev_b32_e32 v26, 16, v17
	v_and_b32_e32 v27, 0xffff0000, v17
	v_mul_f32_e32 v24, 0xbfb8aa3b, v24
	v_mul_f32_e32 v25, 0xbfb8aa3b, v25
	v_mul_f32_e32 v26, 0xbfb8aa3b, v26
	v_mul_f32_e32 v27, 0xbfb8aa3b, v27
	v_exp_f32_e32 v24, v24
	v_exp_f32_e32 v25, v25
	v_exp_f32_e32 v26, v26
	v_exp_f32_e32 v27, v27
	s_nop 0
	v_add_f32_e32 v24, 1.0, v24
	v_add_f32_e32 v25, 1.0, v25
	v_add_f32_e32 v26, 1.0, v26
	v_add_f32_e32 v27, 1.0, v27
	v_rcp_f32_e32 v24, v24
	v_rcp_f32_e32 v25, v25
	v_rcp_f32_e32 v26, v26
	v_rcp_f32_e32 v27, v27
	s_nop 0
	v_pk_mul_f32 v[4:5], v[4:5], v[24:25]
	v_pk_mul_f32 v[6:7], v[6:7], v[26:27]
	v_lshlrev_b32_e32 v24, 16, v18
	v_and_b32_e32 v25, 0xffff0000, v18
	v_lshlrev_b32_e32 v26, 16, v19
	v_and_b32_e32 v27, 0xffff0000, v19
	v_mul_f32_e32 v24, 0xbfb8aa3b, v24
	v_mul_f32_e32 v25, 0xbfb8aa3b, v25
	v_mul_f32_e32 v26, 0xbfb8aa3b, v26
	v_mul_f32_e32 v27, 0xbfb8aa3b, v27
	v_exp_f32_e32 v24, v24
	v_exp_f32_e32 v25, v25
	v_exp_f32_e32 v26, v26
	v_exp_f32_e32 v27, v27
	s_nop 0
	v_add_f32_e32 v24, 1.0, v24
	v_add_f32_e32 v25, 1.0, v25
	v_add_f32_e32 v26, 1.0, v26
	v_add_f32_e32 v27, 1.0, v27
	v_rcp_f32_e32 v24, v24
	v_rcp_f32_e32 v25, v25
	v_rcp_f32_e32 v26, v26
	v_rcp_f32_e32 v27, v27
	s_nop 0
	v_pk_mul_f32 v[8:9], v[8:9], v[24:25]
	v_pk_mul_f32 v[10:11], v[10:11], v[26:27]
	v_lshlrev_b32_e32 v24, 16, v20
	v_and_b32_e32 v25, 0xffff0000, v20
	v_lshlrev_b32_e32 v26, 16, v21
	v_and_b32_e32 v27, 0xffff0000, v21
	v_mul_f32_e32 v24, 0xbfb8aa3b, v24
	v_mul_f32_e32 v25, 0xbfb8aa3b, v25
	v_mul_f32_e32 v26, 0xbfb8aa3b, v26
	v_mul_f32_e32 v27, 0xbfb8aa3b, v27
	v_exp_f32_e32 v24, v24
	v_exp_f32_e32 v25, v25
	v_exp_f32_e32 v26, v26
	v_exp_f32_e32 v27, v27
	s_nop 0
	v_add_f32_e32 v24, 1.0, v24
	v_add_f32_e32 v25, 1.0, v25
	v_add_f32_e32 v26, 1.0, v26
	v_add_f32_e32 v27, 1.0, v27
	v_rcp_f32_e32 v24, v24
	v_rcp_f32_e32 v25, v25
	v_rcp_f32_e32 v26, v26
	v_rcp_f32_e32 v27, v27
	s_nop 0
	v_pk_mul_f32 v[12:13], v[12:13], v[24:25]
	v_pk_mul_f32 v[14:15], v[14:15], v[26:27]
	v_pk_add_f32 v[4:5], v[8:9], v[4:5]
	v_pk_add_f32 v[6:7], v[10:11], v[6:7]
	v_pk_add_f32 v[4:5], v[12:13], v[4:5]
	v_pk_add_f32 v[6:7], v[14:15], v[6:7]
	s_nop 0
	v_cvt_pk_bf16_f32 v4, v4, v5
	v_cvt_pk_bf16_f32 v5, v6, v7
	global_store_dwordx2 v3, v[4:5], s[98:99]
